# GEMM K-loops: LDS-DMA loads use SGPR base + 32-bit lane offset (saddr form) instead of per-load 64-bit VALU address adds
# speedup vs baseline: 1.0037x; 1.0000x over previous
.LBB0_131:
	s_add_u32 s28, s8, s10
	s_addc_u32 s29, s9, s11
	s_add_u32 s34, s28, 0x100
	s_addc_u32 s35, s29, 0
	s_add_u32 s30, s70, s10
	s_addc_u32 s31, s71, s11
	s_add_u32 s28, s28, 0x180
	s_addc_u32 s29, s29, 0
	s_add_i32 s73, 0, 0x10000
	s_add_i32 s76, 0, 0x14000
	v_add_u32_e32 v146, s73, v166
	ds_read_b128 v[148:151], v146
	ds_read_b128 v[152:155], v146 offset:1024
	ds_read_b128 v[156:159], v146 offset:2048
	ds_read_b128 v[160:163], v146 offset:3072
	v_add_u32_e32 v146, s76, v166
	ds_read_b128 v[172:175], v146
	ds_read_b128 v[176:179], v146 offset:1024
	ds_read_b128 v[180:183], v146 offset:2048
	ds_read_b128 v[184:187], v146 offset:3072
	s_cmpk_eq_i32 s10, 0x700
	s_cselect_b32 s29, s69, s29
	s_cselect_b32 s28, s68, s28
	s_cselect_b32 s31, s21, s31
	s_cselect_b32 s30, s59, s30
	s_cselect_b32 s35, s23, s35
	s_cselect_b32 s34, s58, s34
	v_lshl_add_u64 v[164:165], v[142:143], 0, s[10:11]
	s_add_i32 m0, s41, 0xc000
	ds_read_b128 v[188:191], v171
	ds_read_b128 v[202:205], v171 offset:1024
	ds_read_b128 v[206:209], v171 offset:2048
	ds_read_b128 v[210:213], v171 offset:3072
	ds_read_b128 v[214:217], v171 offset:4096
	ds_read_b128 v[218:221], v171 offset:5120
	ds_read_b128 v[222:225], v171 offset:6144
	ds_read_b128 v[226:229], v171 offset:7168
	global_load_lds_dwordx4 v[164:165], off
	v_lshl_add_u64 v[164:165], v[144:145], 0, s[10:11]
	s_add_i32 m0, s41, 0xe000
	s_nop 0
	global_load_lds_dwordx4 v[164:165], off
	s_waitcnt vmcnt(8)
	s_waitcnt lgkmcnt(0)
	s_barrier
	s_setprio 1
	s_waitcnt lgkmcnt(0)
	v_mfma_f32_16x16x32_bf16 v[126:129], v[148:151], v[188:191], v[126:129]
	v_mfma_f32_16x16x32_bf16 v[122:125], v[156:159], v[188:191], v[122:125]
	v_mfma_f32_16x16x32_bf16 v[110:113], v[148:151], v[206:209], v[110:113]
	v_mfma_f32_16x16x32_bf16 v[106:109], v[156:159], v[206:209], v[106:109]
	v_mfma_f32_16x16x32_bf16 v[94:97], v[148:151], v[214:217], v[94:97]
	v_mfma_f32_16x16x32_bf16 v[90:93], v[156:159], v[214:217], v[90:93]
	v_mfma_f32_16x16x32_bf16 v[78:81], v[148:151], v[222:225], v[78:81]
	v_mfma_f32_16x16x32_bf16 v[74:77], v[156:159], v[222:225], v[74:77]
	v_mfma_f32_16x16x32_bf16 v[126:129], v[152:155], v[202:205], v[126:129]
	v_mfma_f32_16x16x32_bf16 v[122:125], v[160:163], v[202:205], v[122:125]
	v_mfma_f32_16x16x32_bf16 v[110:113], v[152:155], v[210:213], v[110:113]
	v_mfma_f32_16x16x32_bf16 v[106:109], v[160:163], v[210:213], v[106:109]
	v_mfma_f32_16x16x32_bf16 v[94:97], v[152:155], v[218:221], v[94:97]
	v_mfma_f32_16x16x32_bf16 v[90:93], v[160:163], v[218:221], v[90:93]
	v_mfma_f32_16x16x32_bf16 v[78:81], v[152:155], v[226:229], v[78:81]
	v_mfma_f32_16x16x32_bf16 v[74:77], v[160:163], v[226:229], v[74:77]
	s_setprio 0
	s_setprio 1
	v_mfma_f32_16x16x32_bf16 v[118:121], v[172:175], v[188:191], v[118:121]
	v_mfma_f32_16x16x32_bf16 v[114:117], v[180:183], v[188:191], v[114:117]
	v_mfma_f32_16x16x32_bf16 v[102:105], v[172:175], v[206:209], v[102:105]
	v_mfma_f32_16x16x32_bf16 v[98:101], v[180:183], v[206:209], v[98:101]
	v_mfma_f32_16x16x32_bf16 v[86:89], v[172:175], v[214:217], v[86:89]
	v_mfma_f32_16x16x32_bf16 v[82:85], v[180:183], v[214:217], v[82:85]
	v_mfma_f32_16x16x32_bf16 v[70:73], v[172:175], v[222:225], v[70:73]
	v_mfma_f32_16x16x32_bf16 v[66:69], v[180:183], v[222:225], v[66:69]
	v_mfma_f32_16x16x32_bf16 v[118:121], v[176:179], v[202:205], v[118:121]
	v_mfma_f32_16x16x32_bf16 v[114:117], v[184:187], v[202:205], v[114:117]
	v_mfma_f32_16x16x32_bf16 v[102:105], v[176:179], v[210:213], v[102:105]
	v_mfma_f32_16x16x32_bf16 v[98:101], v[184:187], v[210:213], v[98:101]
	v_mfma_f32_16x16x32_bf16 v[86:89], v[176:179], v[218:221], v[86:89]
	v_mfma_f32_16x16x32_bf16 v[82:85], v[184:187], v[218:221], v[82:85]
	v_mfma_f32_16x16x32_bf16 v[70:73], v[176:179], v[226:229], v[70:73]
	v_mfma_f32_16x16x32_bf16 v[66:69], v[184:187], v[226:229], v[66:69]
	s_setprio 0
	s_barrier
	s_add_i32 s73, s73, s40
	v_lshl_add_u64 v[164:165], s[30:31], 0, v[134:135]
	s_mov_b32 m0, s73
	ds_read_b128 v[188:191], v171 offset:16384
	ds_read_b128 v[202:205], v171 offset:17408
	ds_read_b128 v[206:209], v171 offset:18432
	ds_read_b128 v[210:213], v171 offset:19456
	ds_read_b128 v[214:217], v171 offset:20480
	ds_read_b128 v[218:221], v171 offset:21504
	ds_read_b128 v[222:225], v171 offset:22528
	ds_read_b128 v[226:229], v171 offset:23552
	global_load_lds_dwordx4 v[164:165], off
	s_add_i32 m0, s73, 0x2000
	s_add_u32 s74, s30, 0x40000
	v_lshl_add_u64 v[192:193], s[30:31], 0, v[130:131]
	s_addc_u32 s75, s31, 0
	s_add_i32 s73, s76, s40
	global_load_lds_dwordx4 v[192:193], off
	s_mov_b32 m0, s73
	s_nop 0
	global_load_lds_dwordx4 v134, s[74:75]
	s_add_i32 m0, s73, 0x2000
	s_nop 0
	global_load_lds_dwordx4 v130, s[74:75]
	s_mov_b32 m0, s41
	s_nop 0
	global_load_lds_dwordx4 v136, s[34:35]
	s_mov_b32 m0, s42
	s_nop 0
	global_load_lds_dwordx4 v132, s[34:35]
	s_waitcnt vmcnt(8)
	s_waitcnt lgkmcnt(0)
	s_barrier
	s_setprio 1
	s_waitcnt lgkmcnt(0)
	v_mfma_f32_16x16x32_bf16 v[62:65], v[148:151], v[188:191], v[62:65]
	v_mfma_f32_16x16x32_bf16 v[58:61], v[156:159], v[188:191], v[58:61]
	v_mfma_f32_16x16x32_bf16 v[46:49], v[148:151], v[206:209], v[46:49]
	v_mfma_f32_16x16x32_bf16 v[42:45], v[156:159], v[206:209], v[42:45]
	v_mfma_f32_16x16x32_bf16 v[30:33], v[148:151], v[214:217], v[30:33]
	v_mfma_f32_16x16x32_bf16 v[26:29], v[156:159], v[214:217], v[26:29]
	v_mfma_f32_16x16x32_bf16 v[14:17], v[148:151], v[222:225], v[14:17]
	v_mfma_f32_16x16x32_bf16 v[10:13], v[156:159], v[222:225], v[10:13]
	v_mfma_f32_16x16x32_bf16 v[62:65], v[152:155], v[202:205], v[62:65]
	v_mfma_f32_16x16x32_bf16 v[58:61], v[160:163], v[202:205], v[58:61]
	v_mfma_f32_16x16x32_bf16 v[46:49], v[152:155], v[210:213], v[46:49]
	v_mfma_f32_16x16x32_bf16 v[42:45], v[160:163], v[210:213], v[42:45]
	v_mfma_f32_16x16x32_bf16 v[30:33], v[152:155], v[218:221], v[30:33]
	v_mfma_f32_16x16x32_bf16 v[26:29], v[160:163], v[218:221], v[26:29]
	v_mfma_f32_16x16x32_bf16 v[14:17], v[152:155], v[226:229], v[14:17]
	v_mfma_f32_16x16x32_bf16 v[10:13], v[160:163], v[226:229], v[10:13]
	s_setprio 0
	s_setprio 1
	v_mfma_f32_16x16x32_bf16 v[54:57], v[172:175], v[188:191], v[54:57]
	v_mfma_f32_16x16x32_bf16 v[50:53], v[180:183], v[188:191], v[50:53]
	v_mfma_f32_16x16x32_bf16 v[38:41], v[172:175], v[206:209], v[38:41]
	v_mfma_f32_16x16x32_bf16 v[34:37], v[180:183], v[206:209], v[34:37]
	v_mfma_f32_16x16x32_bf16 v[22:25], v[172:175], v[214:217], v[22:25]
	v_mfma_f32_16x16x32_bf16 v[18:21], v[180:183], v[214:217], v[18:21]
	v_mfma_f32_16x16x32_bf16 v[6:9], v[172:175], v[222:225], v[6:9]
	v_mfma_f32_16x16x32_bf16 v[2:5], v[180:183], v[222:225], v[2:5]
	v_mfma_f32_16x16x32_bf16 v[54:57], v[176:179], v[202:205], v[54:57]
	v_mfma_f32_16x16x32_bf16 v[50:53], v[184:187], v[202:205], v[50:53]
	v_mfma_f32_16x16x32_bf16 v[38:41], v[176:179], v[210:213], v[38:41]
	v_mfma_f32_16x16x32_bf16 v[34:37], v[184:187], v[210:213], v[34:37]
	v_mfma_f32_16x16x32_bf16 v[22:25], v[176:179], v[218:221], v[22:25]
	v_mfma_f32_16x16x32_bf16 v[18:21], v[184:187], v[218:221], v[18:21]
	v_mfma_f32_16x16x32_bf16 v[6:9], v[176:179], v[226:229], v[6:9]
	v_mfma_f32_16x16x32_bf16 v[2:5], v[184:187], v[226:229], v[2:5]
	s_setprio 0
	s_barrier
	s_add_i32 s73, 0, 0x18000
	v_add_u32_e32 v146, s73, v166
	s_add_i32 s74, 0, 0x1c000
	ds_read_b128 v[148:151], v146
	ds_read_b128 v[152:155], v146 offset:1024
	ds_read_b128 v[156:159], v146 offset:2048
	ds_read_b128 v[160:163], v146 offset:3072
	v_add_u32_e32 v146, s74, v166
	ds_read_b128 v[172:175], v146
	ds_read_b128 v[176:179], v146 offset:1024
	ds_read_b128 v[180:183], v146 offset:2048
	ds_read_b128 v[184:187], v146 offset:3072
	s_add_u32 s34, s34, 0x40000
	s_addc_u32 s35, s35, 0
	s_mov_b32 m0, s43
	ds_read_b128 v[188:191], v171 offset:32768
	ds_read_b128 v[202:205], v171 offset:33792
	ds_read_b128 v[206:209], v171 offset:34816
	ds_read_b128 v[210:213], v171 offset:35840
	ds_read_b128 v[214:217], v171 offset:36864
	ds_read_b128 v[218:221], v171 offset:37888
	ds_read_b128 v[222:225], v171 offset:38912
	ds_read_b128 v[226:229], v171 offset:39936
	global_load_lds_dwordx4 v136, s[34:35]
	s_mov_b32 m0, s44
	s_nop 0
	global_load_lds_dwordx4 v132, s[34:35]
	s_waitcnt vmcnt(8)
	s_waitcnt lgkmcnt(0)
	s_barrier
	s_setprio 1
	s_waitcnt lgkmcnt(0)
	v_mfma_f32_16x16x32_bf16 v[126:129], v[148:151], v[188:191], v[126:129]
	v_mfma_f32_16x16x32_bf16 v[122:125], v[156:159], v[188:191], v[122:125]
	v_mfma_f32_16x16x32_bf16 v[110:113], v[148:151], v[206:209], v[110:113]
	v_mfma_f32_16x16x32_bf16 v[106:109], v[156:159], v[206:209], v[106:109]
	v_mfma_f32_16x16x32_bf16 v[94:97], v[148:151], v[214:217], v[94:97]
	v_mfma_f32_16x16x32_bf16 v[90:93], v[156:159], v[214:217], v[90:93]
	v_mfma_f32_16x16x32_bf16 v[78:81], v[148:151], v[222:225], v[78:81]
	v_mfma_f32_16x16x32_bf16 v[74:77], v[156:159], v[222:225], v[74:77]
	v_mfma_f32_16x16x32_bf16 v[126:129], v[152:155], v[202:205], v[126:129]
	v_mfma_f32_16x16x32_bf16 v[122:125], v[160:163], v[202:205], v[122:125]
	v_mfma_f32_16x16x32_bf16 v[110:113], v[152:155], v[210:213], v[110:113]
	v_mfma_f32_16x16x32_bf16 v[106:109], v[160:163], v[210:213], v[106:109]
	v_mfma_f32_16x16x32_bf16 v[94:97], v[152:155], v[218:221], v[94:97]
	v_mfma_f32_16x16x32_bf16 v[90:93], v[160:163], v[218:221], v[90:93]
	v_mfma_f32_16x16x32_bf16 v[78:81], v[152:155], v[226:229], v[78:81]
	v_mfma_f32_16x16x32_bf16 v[74:77], v[160:163], v[226:229], v[74:77]
	s_setprio 0
	s_setprio 1
	v_mfma_f32_16x16x32_bf16 v[118:121], v[172:175], v[188:191], v[118:121]
	v_mfma_f32_16x16x32_bf16 v[114:117], v[180:183], v[188:191], v[114:117]
	v_mfma_f32_16x16x32_bf16 v[102:105], v[172:175], v[206:209], v[102:105]
	v_mfma_f32_16x16x32_bf16 v[98:101], v[180:183], v[206:209], v[98:101]
	v_mfma_f32_16x16x32_bf16 v[86:89], v[172:175], v[214:217], v[86:89]
	v_mfma_f32_16x16x32_bf16 v[82:85], v[180:183], v[214:217], v[82:85]
	v_mfma_f32_16x16x32_bf16 v[70:73], v[172:175], v[222:225], v[70:73]
	v_mfma_f32_16x16x32_bf16 v[66:69], v[180:183], v[222:225], v[66:69]
	v_mfma_f32_16x16x32_bf16 v[118:121], v[176:179], v[202:205], v[118:121]
	v_mfma_f32_16x16x32_bf16 v[114:117], v[184:187], v[202:205], v[114:117]
	v_mfma_f32_16x16x32_bf16 v[102:105], v[176:179], v[210:213], v[102:105]
	v_mfma_f32_16x16x32_bf16 v[98:101], v[184:187], v[210:213], v[98:101]
	v_mfma_f32_16x16x32_bf16 v[86:89], v[176:179], v[218:221], v[86:89]
	v_mfma_f32_16x16x32_bf16 v[82:85], v[184:187], v[218:221], v[82:85]
	v_mfma_f32_16x16x32_bf16 v[70:73], v[176:179], v[226:229], v[70:73]
	v_mfma_f32_16x16x32_bf16 v[66:69], v[184:187], v[226:229], v[66:69]
	s_setprio 0
	s_barrier
	s_add_i32 s34, s73, s40
	v_lshl_add_u64 v[164:165], v[164:165], 0, s[90:91]
	s_mov_b32 m0, s34
	ds_read_b128 v[188:191], v171 offset:49152
	ds_read_b128 v[202:205], v171 offset:50176
	ds_read_b128 v[206:209], v171 offset:51200
	ds_read_b128 v[210:213], v171 offset:52224
	ds_read_b128 v[214:217], v171 offset:53248
	ds_read_b128 v[218:221], v171 offset:54272
	ds_read_b128 v[222:225], v171 offset:55296
	ds_read_b128 v[226:229], v171 offset:56320
	global_load_lds_dwordx4 v[164:165], off
	s_add_i32 m0, s34, 0x2000
	s_add_u32 s30, s30, 0x40080
	v_lshl_add_u64 v[164:165], v[192:193], 0, s[90:91]
	s_addc_u32 s31, s31, 0
	s_add_i32 s34, s74, s40
	global_load_lds_dwordx4 v[164:165], off
	s_mov_b32 m0, s34
	s_nop 0
	global_load_lds_dwordx4 v134, s[30:31]
	s_add_i32 m0, s34, 0x2000
	s_nop 0
	global_load_lds_dwordx4 v130, s[30:31]
	s_mov_b32 m0, s45
	s_nop 0
	global_load_lds_dwordx4 v136, s[28:29]
	s_mov_b32 m0, s51
	s_nop 0
	global_load_lds_dwordx4 v132, s[28:29]
	s_waitcnt vmcnt(8)
	s_waitcnt lgkmcnt(0)
	s_barrier
	s_setprio 1
	s_waitcnt lgkmcnt(0)
	v_mfma_f32_16x16x32_bf16 v[62:65], v[148:151], v[188:191], v[62:65]
	v_mfma_f32_16x16x32_bf16 v[58:61], v[156:159], v[188:191], v[58:61]
	v_mfma_f32_16x16x32_bf16 v[46:49], v[148:151], v[206:209], v[46:49]
	v_mfma_f32_16x16x32_bf16 v[42:45], v[156:159], v[206:209], v[42:45]
	v_mfma_f32_16x16x32_bf16 v[30:33], v[148:151], v[214:217], v[30:33]
	v_mfma_f32_16x16x32_bf16 v[26:29], v[156:159], v[214:217], v[26:29]
	v_mfma_f32_16x16x32_bf16 v[14:17], v[148:151], v[222:225], v[14:17]
	v_mfma_f32_16x16x32_bf16 v[10:13], v[156:159], v[222:225], v[10:13]
	v_mfma_f32_16x16x32_bf16 v[62:65], v[152:155], v[202:205], v[62:65]
	v_mfma_f32_16x16x32_bf16 v[58:61], v[160:163], v[202:205], v[58:61]
	v_mfma_f32_16x16x32_bf16 v[46:49], v[152:155], v[210:213], v[46:49]
	v_mfma_f32_16x16x32_bf16 v[42:45], v[160:163], v[210:213], v[42:45]
	v_mfma_f32_16x16x32_bf16 v[30:33], v[152:155], v[218:221], v[30:33]
	v_mfma_f32_16x16x32_bf16 v[26:29], v[160:163], v[218:221], v[26:29]
	v_mfma_f32_16x16x32_bf16 v[14:17], v[152:155], v[226:229], v[14:17]
	v_mfma_f32_16x16x32_bf16 v[10:13], v[160:163], v[226:229], v[10:13]
	s_setprio 0
	s_setprio 1
	v_mfma_f32_16x16x32_bf16 v[54:57], v[172:175], v[188:191], v[54:57]
	v_mfma_f32_16x16x32_bf16 v[50:53], v[180:183], v[188:191], v[50:53]
	v_mfma_f32_16x16x32_bf16 v[38:41], v[172:175], v[206:209], v[38:41]
	v_mfma_f32_16x16x32_bf16 v[34:37], v[180:183], v[206:209], v[34:37]
	v_mfma_f32_16x16x32_bf16 v[22:25], v[172:175], v[214:217], v[22:25]
	v_mfma_f32_16x16x32_bf16 v[18:21], v[180:183], v[214:217], v[18:21]
	v_mfma_f32_16x16x32_bf16 v[6:9], v[172:175], v[222:225], v[6:9]
	v_mfma_f32_16x16x32_bf16 v[2:5], v[180:183], v[222:225], v[2:5]
	v_mfma_f32_16x16x32_bf16 v[54:57], v[176:179], v[202:205], v[54:57]
	v_mfma_f32_16x16x32_bf16 v[50:53], v[184:187], v[202:205], v[50:53]
	v_mfma_f32_16x16x32_bf16 v[38:41], v[176:179], v[210:213], v[38:41]
	v_mfma_f32_16x16x32_bf16 v[34:37], v[184:187], v[210:213], v[34:37]
	v_mfma_f32_16x16x32_bf16 v[22:25], v[176:179], v[218:221], v[22:25]
	v_mfma_f32_16x16x32_bf16 v[18:21], v[184:187], v[218:221], v[18:21]
	v_mfma_f32_16x16x32_bf16 v[6:9], v[176:179], v[226:229], v[6:9]
	v_mfma_f32_16x16x32_bf16 v[2:5], v[184:187], v[226:229], v[2:5]
	s_setprio 0
	s_barrier
	s_add_i32 s72, s72, 2
	s_add_u32 s10, s10, 0x100
	s_addc_u32 s11, s11, 0
	s_cmp_gt_u32 s72, 13
	s_cbranch_scc0 .LBB0_131
	s_and_b64 vcc, exec, s[18:19]
	s_cbranch_vccz .LBB0_134
	s_barrier

.LBB0_345:
	s_add_u32 s34, s28, s30
	s_addc_u32 s35, s29, s31
	s_add_u32 s38, s34, 0x100
	s_addc_u32 s39, s35, 0
	s_add_u32 s36, s75, s30
	s_addc_u32 s37, s76, s31
	s_add_u32 s34, s34, 0x180
	s_addc_u32 s35, s35, 0
	s_add_i32 s85, 0, 0x10000
	s_add_i32 vcc_lo, 0, 0x14000
	v_add_u32_e32 v0, s85, v152
	ds_read_b128 v[148:151], v0
	ds_read_b128 v[154:157], v0 offset:1024
	ds_read_b128 v[158:161], v0 offset:2048
	ds_read_b128 v[162:165], v0 offset:3072
	v_add_u32_e32 v0, vcc_lo, v152
	ds_read_b128 v[166:169], v0
	ds_read_b128 v[170:173], v0 offset:1024
	ds_read_b128 v[174:177], v0 offset:2048
	ds_read_b128 v[178:181], v0 offset:3072
	s_cmpk_eq_i32 s30, 0x700
	s_cselect_b32 s35, s74, s35
	s_cselect_b32 s34, s73, s34
	s_cselect_b32 s37, s21, s37
	s_cselect_b32 s36, s72, s36
	s_cselect_b32 s39, s23, s39
	s_cselect_b32 s38, s71, s38
	v_lshl_add_u64 v[194:195], v[144:145], 0, s[30:31]
	s_add_i32 m0, s45, 0xc000
	ds_read_b128 v[182:185], v153
	ds_read_b128 v[186:189], v153 offset:1024
	ds_read_b128 v[190:193], v153 offset:2048
	ds_read_b128 v[202:205], v153 offset:3072
	ds_read_b128 v[206:209], v153 offset:4096
	ds_read_b128 v[210:213], v153 offset:5120
	ds_read_b128 v[214:217], v153 offset:6144
	ds_read_b128 v[218:221], v153 offset:7168
	global_load_lds_dwordx4 v[194:195], off
	v_lshl_add_u64 v[194:195], v[146:147], 0, s[30:31]
	s_add_i32 m0, s45, 0xe000
	s_nop 0
	global_load_lds_dwordx4 v[194:195], off
	s_waitcnt vmcnt(8)
	s_waitcnt lgkmcnt(0)
	s_barrier
	s_setprio 1
	s_waitcnt lgkmcnt(0)
	v_mfma_f32_16x16x32_bf16 v[126:129], v[148:151], v[182:185], v[126:129]
	v_mfma_f32_16x16x32_bf16 v[122:125], v[158:161], v[182:185], v[122:125]
	v_mfma_f32_16x16x32_bf16 v[110:113], v[148:151], v[190:193], v[110:113]
	v_mfma_f32_16x16x32_bf16 v[106:109], v[158:161], v[190:193], v[106:109]
	v_mfma_f32_16x16x32_bf16 v[94:97], v[148:151], v[206:209], v[94:97]
	v_mfma_f32_16x16x32_bf16 v[90:93], v[158:161], v[206:209], v[90:93]
	v_mfma_f32_16x16x32_bf16 v[78:81], v[148:151], v[214:217], v[78:81]
	v_mfma_f32_16x16x32_bf16 v[74:77], v[158:161], v[214:217], v[74:77]
	v_mfma_f32_16x16x32_bf16 v[126:129], v[154:157], v[186:189], v[126:129]
	v_mfma_f32_16x16x32_bf16 v[122:125], v[162:165], v[186:189], v[122:125]
	v_mfma_f32_16x16x32_bf16 v[110:113], v[154:157], v[202:205], v[110:113]
	v_mfma_f32_16x16x32_bf16 v[106:109], v[162:165], v[202:205], v[106:109]
	v_mfma_f32_16x16x32_bf16 v[94:97], v[154:157], v[210:213], v[94:97]
	v_mfma_f32_16x16x32_bf16 v[90:93], v[162:165], v[210:213], v[90:93]
	v_mfma_f32_16x16x32_bf16 v[78:81], v[154:157], v[218:221], v[78:81]
	v_mfma_f32_16x16x32_bf16 v[74:77], v[162:165], v[218:221], v[74:77]
	s_setprio 0
	s_setprio 1
	v_mfma_f32_16x16x32_bf16 v[118:121], v[166:169], v[182:185], v[118:121]
	v_mfma_f32_16x16x32_bf16 v[114:117], v[174:177], v[182:185], v[114:117]
	v_mfma_f32_16x16x32_bf16 v[102:105], v[166:169], v[190:193], v[102:105]
	v_mfma_f32_16x16x32_bf16 v[98:101], v[174:177], v[190:193], v[98:101]
	v_mfma_f32_16x16x32_bf16 v[86:89], v[166:169], v[206:209], v[86:89]
	v_mfma_f32_16x16x32_bf16 v[82:85], v[174:177], v[206:209], v[82:85]
	v_mfma_f32_16x16x32_bf16 v[70:73], v[166:169], v[214:217], v[70:73]
	v_mfma_f32_16x16x32_bf16 v[66:69], v[174:177], v[214:217], v[66:69]
	v_mfma_f32_16x16x32_bf16 v[118:121], v[170:173], v[186:189], v[118:121]
	v_mfma_f32_16x16x32_bf16 v[114:117], v[178:181], v[186:189], v[114:117]
	v_mfma_f32_16x16x32_bf16 v[102:105], v[170:173], v[202:205], v[102:105]
	v_mfma_f32_16x16x32_bf16 v[98:101], v[178:181], v[202:205], v[98:101]
	v_mfma_f32_16x16x32_bf16 v[86:89], v[170:173], v[210:213], v[86:89]
	v_mfma_f32_16x16x32_bf16 v[82:85], v[178:181], v[210:213], v[82:85]
	v_mfma_f32_16x16x32_bf16 v[70:73], v[170:173], v[218:221], v[70:73]
	v_mfma_f32_16x16x32_bf16 v[66:69], v[178:181], v[218:221], v[66:69]
	s_setprio 0
	s_barrier
	s_add_i32 s85, s85, s44
	v_lshl_add_u64 v[194:195], s[36:37], 0, v[134:135]
	s_mov_b32 m0, s85
	ds_read_b128 v[182:185], v153 offset:16384
	ds_read_b128 v[186:189], v153 offset:17408
	ds_read_b128 v[190:193], v153 offset:18432
	ds_read_b128 v[202:205], v153 offset:19456
	ds_read_b128 v[206:209], v153 offset:20480
	ds_read_b128 v[210:213], v153 offset:21504
	ds_read_b128 v[214:217], v153 offset:22528
	ds_read_b128 v[218:221], v153 offset:23552
	global_load_lds_dwordx4 v[194:195], off
	s_add_i32 m0, s85, 0x2000
	s_add_u32 s86, s36, 0x40000
	v_lshl_add_u64 v[198:199], s[36:37], 0, v[130:131]
	s_addc_u32 s87, s37, 0
	s_add_i32 s85, vcc_lo, s44
	global_load_lds_dwordx4 v[198:199], off
	s_mov_b32 m0, s85
	s_nop 0
	global_load_lds_dwordx4 v134, s[86:87]
	s_add_i32 m0, s85, 0x2000
	s_nop 0
	global_load_lds_dwordx4 v130, s[86:87]
	s_mov_b32 m0, s45
	s_nop 0
	global_load_lds_dwordx4 v136, s[38:39]
	s_mov_b32 m0, s51
	s_nop 0
	global_load_lds_dwordx4 v132, s[38:39]
	s_waitcnt vmcnt(8)
	s_waitcnt lgkmcnt(0)
	s_barrier
	s_setprio 1
	s_waitcnt lgkmcnt(0)
	v_mfma_f32_16x16x32_bf16 v[62:65], v[148:151], v[182:185], v[62:65]
	v_mfma_f32_16x16x32_bf16 v[58:61], v[158:161], v[182:185], v[58:61]
	v_mfma_f32_16x16x32_bf16 v[46:49], v[148:151], v[190:193], v[46:49]
	v_mfma_f32_16x16x32_bf16 v[42:45], v[158:161], v[190:193], v[42:45]
	v_mfma_f32_16x16x32_bf16 v[30:33], v[148:151], v[206:209], v[30:33]
	v_mfma_f32_16x16x32_bf16 v[26:29], v[158:161], v[206:209], v[26:29]
	v_mfma_f32_16x16x32_bf16 v[14:17], v[148:151], v[214:217], v[14:17]
	v_mfma_f32_16x16x32_bf16 v[10:13], v[158:161], v[214:217], v[10:13]
	v_mfma_f32_16x16x32_bf16 v[62:65], v[154:157], v[186:189], v[62:65]
	v_mfma_f32_16x16x32_bf16 v[58:61], v[162:165], v[186:189], v[58:61]
	v_mfma_f32_16x16x32_bf16 v[46:49], v[154:157], v[202:205], v[46:49]
	v_mfma_f32_16x16x32_bf16 v[42:45], v[162:165], v[202:205], v[42:45]
	v_mfma_f32_16x16x32_bf16 v[30:33], v[154:157], v[210:213], v[30:33]
	v_mfma_f32_16x16x32_bf16 v[26:29], v[162:165], v[210:213], v[26:29]
	v_mfma_f32_16x16x32_bf16 v[14:17], v[154:157], v[218:221], v[14:17]
	v_mfma_f32_16x16x32_bf16 v[10:13], v[162:165], v[218:221], v[10:13]
	s_setprio 0
	s_setprio 1
	v_mfma_f32_16x16x32_bf16 v[54:57], v[166:169], v[182:185], v[54:57]
	v_mfma_f32_16x16x32_bf16 v[50:53], v[174:177], v[182:185], v[50:53]
	v_mfma_f32_16x16x32_bf16 v[38:41], v[166:169], v[190:193], v[38:41]
	v_mfma_f32_16x16x32_bf16 v[34:37], v[174:177], v[190:193], v[34:37]
	v_mfma_f32_16x16x32_bf16 v[22:25], v[166:169], v[206:209], v[22:25]
	v_mfma_f32_16x16x32_bf16 v[18:21], v[174:177], v[206:209], v[18:21]
	v_mfma_f32_16x16x32_bf16 v[6:9], v[166:169], v[214:217], v[6:9]
	v_mfma_f32_16x16x32_bf16 v[2:5], v[174:177], v[214:217], v[2:5]
	v_mfma_f32_16x16x32_bf16 v[54:57], v[170:173], v[186:189], v[54:57]
	v_mfma_f32_16x16x32_bf16 v[50:53], v[178:181], v[186:189], v[50:53]
	v_mfma_f32_16x16x32_bf16 v[38:41], v[170:173], v[202:205], v[38:41]
	v_mfma_f32_16x16x32_bf16 v[34:37], v[178:181], v[202:205], v[34:37]
	v_mfma_f32_16x16x32_bf16 v[22:25], v[170:173], v[210:213], v[22:25]
	v_mfma_f32_16x16x32_bf16 v[18:21], v[178:181], v[210:213], v[18:21]
	v_mfma_f32_16x16x32_bf16 v[6:9], v[170:173], v[218:221], v[6:9]
	v_mfma_f32_16x16x32_bf16 v[2:5], v[178:181], v[218:221], v[2:5]
	s_setprio 0
	s_barrier
	s_add_i32 s85, 0, 0x18000
	v_add_u32_e32 v0, s85, v152
	s_add_i32 s86, 0, 0x1c000
	ds_read_b128 v[148:151], v0
	ds_read_b128 v[154:157], v0 offset:1024
	ds_read_b128 v[158:161], v0 offset:2048
	ds_read_b128 v[162:165], v0 offset:3072
	v_add_u32_e32 v0, s86, v152
	ds_read_b128 v[166:169], v0
	ds_read_b128 v[170:173], v0 offset:1024
	ds_read_b128 v[174:177], v0 offset:2048
	ds_read_b128 v[178:181], v0 offset:3072
	s_add_u32 s38, s38, 0x40000
	s_addc_u32 s39, s39, 0
	s_mov_b32 m0, s55
	ds_read_b128 v[182:185], v153 offset:32768
	ds_read_b128 v[186:189], v153 offset:33792
	ds_read_b128 v[190:193], v153 offset:34816
	ds_read_b128 v[202:205], v153 offset:35840
	ds_read_b128 v[206:209], v153 offset:36864
	ds_read_b128 v[210:213], v153 offset:37888
	ds_read_b128 v[214:217], v153 offset:38912
	ds_read_b128 v[218:221], v153 offset:39936
	global_load_lds_dwordx4 v136, s[38:39]
	s_mov_b32 m0, s56
	s_nop 0
	global_load_lds_dwordx4 v132, s[38:39]
	s_waitcnt vmcnt(8)
	s_waitcnt lgkmcnt(0)
	s_barrier
	s_setprio 1
	s_waitcnt lgkmcnt(0)
	v_mfma_f32_16x16x32_bf16 v[126:129], v[148:151], v[182:185], v[126:129]
	v_mfma_f32_16x16x32_bf16 v[122:125], v[158:161], v[182:185], v[122:125]
	v_mfma_f32_16x16x32_bf16 v[110:113], v[148:151], v[190:193], v[110:113]
	v_mfma_f32_16x16x32_bf16 v[106:109], v[158:161], v[190:193], v[106:109]
	v_mfma_f32_16x16x32_bf16 v[94:97], v[148:151], v[206:209], v[94:97]
	v_mfma_f32_16x16x32_bf16 v[90:93], v[158:161], v[206:209], v[90:93]
	v_mfma_f32_16x16x32_bf16 v[78:81], v[148:151], v[214:217], v[78:81]
	v_mfma_f32_16x16x32_bf16 v[74:77], v[158:161], v[214:217], v[74:77]
	v_mfma_f32_16x16x32_bf16 v[126:129], v[154:157], v[186:189], v[126:129]
	v_mfma_f32_16x16x32_bf16 v[122:125], v[162:165], v[186:189], v[122:125]
	v_mfma_f32_16x16x32_bf16 v[110:113], v[154:157], v[202:205], v[110:113]
	v_mfma_f32_16x16x32_bf16 v[106:109], v[162:165], v[202:205], v[106:109]
	v_mfma_f32_16x16x32_bf16 v[94:97], v[154:157], v[210:213], v[94:97]
	v_mfma_f32_16x16x32_bf16 v[90:93], v[162:165], v[210:213], v[90:93]
	v_mfma_f32_16x16x32_bf16 v[78:81], v[154:157], v[218:221], v[78:81]
	v_mfma_f32_16x16x32_bf16 v[74:77], v[162:165], v[218:221], v[74:77]
	s_setprio 0
	s_setprio 1
	v_mfma_f32_16x16x32_bf16 v[118:121], v[166:169], v[182:185], v[118:121]
	v_mfma_f32_16x16x32_bf16 v[114:117], v[174:177], v[182:185], v[114:117]
	v_mfma_f32_16x16x32_bf16 v[102:105], v[166:169], v[190:193], v[102:105]
	v_mfma_f32_16x16x32_bf16 v[98:101], v[174:177], v[190:193], v[98:101]
	v_mfma_f32_16x16x32_bf16 v[86:89], v[166:169], v[206:209], v[86:89]
	v_mfma_f32_16x16x32_bf16 v[82:85], v[174:177], v[206:209], v[82:85]
	v_mfma_f32_16x16x32_bf16 v[70:73], v[166:169], v[214:217], v[70:73]
	v_mfma_f32_16x16x32_bf16 v[66:69], v[174:177], v[214:217], v[66:69]
	v_mfma_f32_16x16x32_bf16 v[118:121], v[170:173], v[186:189], v[118:121]
	v_mfma_f32_16x16x32_bf16 v[114:117], v[178:181], v[186:189], v[114:117]
	v_mfma_f32_16x16x32_bf16 v[102:105], v[170:173], v[202:205], v[102:105]
	v_mfma_f32_16x16x32_bf16 v[98:101], v[178:181], v[202:205], v[98:101]
	v_mfma_f32_16x16x32_bf16 v[86:89], v[170:173], v[210:213], v[86:89]
	v_mfma_f32_16x16x32_bf16 v[82:85], v[178:181], v[210:213], v[82:85]
	v_mfma_f32_16x16x32_bf16 v[70:73], v[170:173], v[218:221], v[70:73]
	v_mfma_f32_16x16x32_bf16 v[66:69], v[178:181], v[218:221], v[66:69]
	s_setprio 0
	s_barrier
	s_add_i32 s38, s85, s44
	v_lshl_add_u64 v[194:195], v[194:195], 0, s[90:91]
	s_mov_b32 m0, s38
	ds_read_b128 v[182:185], v153 offset:49152
	ds_read_b128 v[186:189], v153 offset:50176
	ds_read_b128 v[190:193], v153 offset:51200
	ds_read_b128 v[202:205], v153 offset:52224
	ds_read_b128 v[206:209], v153 offset:53248
	ds_read_b128 v[210:213], v153 offset:54272
	ds_read_b128 v[214:217], v153 offset:55296
	ds_read_b128 v[218:221], v153 offset:56320
	global_load_lds_dwordx4 v[194:195], off
	s_add_i32 m0, s38, 0x2000
	s_add_u32 s36, s36, 0x40080
	v_lshl_add_u64 v[194:195], v[198:199], 0, s[90:91]
	s_addc_u32 s37, s37, 0
	s_add_i32 s38, s86, s44
	global_load_lds_dwordx4 v[194:195], off
	s_mov_b32 m0, s38
	s_nop 0
	global_load_lds_dwordx4 v134, s[36:37]
	s_add_i32 m0, s38, 0x2000
	s_nop 0
	global_load_lds_dwordx4 v130, s[36:37]
	s_mov_b32 m0, s58
	s_nop 0
	global_load_lds_dwordx4 v136, s[34:35]
	s_mov_b32 m0, s59
	s_nop 0
	global_load_lds_dwordx4 v132, s[34:35]
	s_waitcnt vmcnt(8)
	s_waitcnt lgkmcnt(0)
	s_barrier
	s_setprio 1
	s_waitcnt lgkmcnt(0)
	v_mfma_f32_16x16x32_bf16 v[62:65], v[148:151], v[182:185], v[62:65]
	v_mfma_f32_16x16x32_bf16 v[58:61], v[158:161], v[182:185], v[58:61]
	v_mfma_f32_16x16x32_bf16 v[46:49], v[148:151], v[190:193], v[46:49]
	v_mfma_f32_16x16x32_bf16 v[42:45], v[158:161], v[190:193], v[42:45]
	v_mfma_f32_16x16x32_bf16 v[30:33], v[148:151], v[206:209], v[30:33]
	v_mfma_f32_16x16x32_bf16 v[26:29], v[158:161], v[206:209], v[26:29]
	v_mfma_f32_16x16x32_bf16 v[14:17], v[148:151], v[214:217], v[14:17]
	v_mfma_f32_16x16x32_bf16 v[10:13], v[158:161], v[214:217], v[10:13]
	v_mfma_f32_16x16x32_bf16 v[62:65], v[154:157], v[186:189], v[62:65]
	v_mfma_f32_16x16x32_bf16 v[58:61], v[162:165], v[186:189], v[58:61]
	v_mfma_f32_16x16x32_bf16 v[46:49], v[154:157], v[202:205], v[46:49]
	v_mfma_f32_16x16x32_bf16 v[42:45], v[162:165], v[202:205], v[42:45]
	v_mfma_f32_16x16x32_bf16 v[30:33], v[154:157], v[210:213], v[30:33]
	v_mfma_f32_16x16x32_bf16 v[26:29], v[162:165], v[210:213], v[26:29]
	v_mfma_f32_16x16x32_bf16 v[14:17], v[154:157], v[218:221], v[14:17]
	v_mfma_f32_16x16x32_bf16 v[10:13], v[162:165], v[218:221], v[10:13]
	s_setprio 0
	s_setprio 1
	v_mfma_f32_16x16x32_bf16 v[54:57], v[166:169], v[182:185], v[54:57]
	v_mfma_f32_16x16x32_bf16 v[50:53], v[174:177], v[182:185], v[50:53]
	v_mfma_f32_16x16x32_bf16 v[38:41], v[166:169], v[190:193], v[38:41]
	v_mfma_f32_16x16x32_bf16 v[34:37], v[174:177], v[190:193], v[34:37]
	v_mfma_f32_16x16x32_bf16 v[22:25], v[166:169], v[206:209], v[22:25]
	v_mfma_f32_16x16x32_bf16 v[18:21], v[174:177], v[206:209], v[18:21]
	v_mfma_f32_16x16x32_bf16 v[6:9], v[166:169], v[214:217], v[6:9]
	v_mfma_f32_16x16x32_bf16 v[2:5], v[174:177], v[214:217], v[2:5]
	v_mfma_f32_16x16x32_bf16 v[54:57], v[170:173], v[186:189], v[54:57]
	v_mfma_f32_16x16x32_bf16 v[50:53], v[178:181], v[186:189], v[50:53]
	v_mfma_f32_16x16x32_bf16 v[38:41], v[170:173], v[202:205], v[38:41]
	v_mfma_f32_16x16x32_bf16 v[34:37], v[178:181], v[202:205], v[34:37]
	v_mfma_f32_16x16x32_bf16 v[22:25], v[170:173], v[210:213], v[22:25]
	v_mfma_f32_16x16x32_bf16 v[18:21], v[178:181], v[210:213], v[18:21]
	v_mfma_f32_16x16x32_bf16 v[6:9], v[170:173], v[218:221], v[6:9]
	v_mfma_f32_16x16x32_bf16 v[2:5], v[178:181], v[218:221], v[2:5]
	s_setprio 0
	s_barrier
	s_add_i32 s78, s78, 2
	s_add_u32 s30, s30, 0x100
	s_addc_u32 s31, s31, 0
	s_cmp_gt_u32 s78, 13
	s_cbranch_scc0 .LBB0_345
	s_and_b64 vcc, exec, s[16:17]
	s_cbranch_vccz .LBB0_348
	s_barrier

.LBB0_541:
	s_add_i32 s78, s78, 2
	s_cmp_gt_u32 s78, 7
	s_cselect_b32 vcc_lo, 0xffffec00, 0
	s_cselect_b32 vcc_hi, -1, 0
	s_cmp_gt_u32 s78, 5
	s_cselect_b32 s11, 0xffffec00, 0
	s_cselect_b32 s10, -1, 0
	s_add_u32 s11, s11, s36
	s_addc_u32 s10, s10, s37
	s_add_u32 s11, s34, s11
	s_addc_u32 s10, s35, s10
	s_add_u32 s11, s11, 0x100
	s_addc_u32 s10, s10, 0
	s_add_u32 s38, s86, s36
	s_addc_u32 s39, s87, s37
	s_cmp_gt_u32 s78, 4
	s_cselect_b32 s41, 0xffffec00, 0
	s_cselect_b32 s40, -1, 0
	s_add_u32 s41, s41, s36
	s_addc_u32 s40, s40, s37
	s_add_u32 s41, s34, s41
	s_addc_u32 s40, s35, s40
	s_add_u32 s4, s41, 0x180
	s_addc_u32 s5, s40, 0
	s_cmpk_eq_i32 s36, 0x700
	s_cselect_b32 s41, s29, s10
	s_cselect_b32 s40, s28, s11
	s_cselect_b32 s39, s73, s39
	s_cselect_b32 s38, s74, s38
	s_cselect_b32 s11, s76, s5
	s_cselect_b32 s10, s75, s4
	s_add_i32 s4, 0, 0x10000
	v_add_u32_e32 v0, s4, v244
	s_add_i32 s5, 0, 0x14000
	ds_read_b128 v[132:135], v0
	ds_read_b128 v[136:139], v0 offset:1024
	ds_read_b128 v[144:147], v0 offset:2048
	ds_read_b128 v[148:151], v0 offset:3072
	v_add_u32_e32 v0, s5, v244
	ds_read_b128 v[152:155], v0
	ds_read_b128 v[156:159], v0 offset:1024
	ds_read_b128 v[160:163], v0 offset:2048
	ds_read_b128 v[164:167], v0 offset:3072
	s_add_u32 vcc_lo, vcc_lo, s36
	s_addc_u32 vcc_hi, vcc_hi, s37
	v_lshl_add_u64 v[2:3], v[140:141], 0, vcc
	s_add_i32 m0, s55, 0xc000
	ds_read_b128 v[168:171], v246
	ds_read_b128 v[172:175], v246 offset:1024
	ds_read_b128 v[176:179], v246 offset:2048
	ds_read_b128 v[180:183], v246 offset:3072
	ds_read_b128 v[184:187], v246 offset:4096
	ds_read_b128 v[188:191], v246 offset:5120
	ds_read_b128 v[212:215], v246 offset:6144
	ds_read_b128 v[216:219], v246 offset:7168
	global_load_lds_dwordx4 v[2:3], off
	v_lshl_add_u64 v[2:3], v[142:143], 0, vcc
	s_add_i32 m0, s55, 0xe000
	s_nop 0
	global_load_lds_dwordx4 v[2:3], off
	s_waitcnt vmcnt(8)
	s_waitcnt lgkmcnt(0)
	s_barrier
	s_setprio 1
	s_waitcnt lgkmcnt(0)
	v_mfma_f32_16x16x32_bf16 v[128:131], v[132:135], v[168:171], v[128:131]
	v_mfma_f32_16x16x32_bf16 v[124:127], v[144:147], v[168:171], v[124:127]
	v_mfma_f32_16x16x32_bf16 v[112:115], v[132:135], v[176:179], v[112:115]
	v_mfma_f32_16x16x32_bf16 v[108:111], v[144:147], v[176:179], v[108:111]
	v_mfma_f32_16x16x32_bf16 v[96:99], v[132:135], v[184:187], v[96:99]
	v_mfma_f32_16x16x32_bf16 v[92:95], v[144:147], v[184:187], v[92:95]
	v_mfma_f32_16x16x32_bf16 v[80:83], v[132:135], v[212:215], v[80:83]
	v_mfma_f32_16x16x32_bf16 v[76:79], v[144:147], v[212:215], v[76:79]
	v_mfma_f32_16x16x32_bf16 v[128:131], v[136:139], v[172:175], v[128:131]
	v_mfma_f32_16x16x32_bf16 v[124:127], v[148:151], v[172:175], v[124:127]
	v_mfma_f32_16x16x32_bf16 v[112:115], v[136:139], v[180:183], v[112:115]
	v_mfma_f32_16x16x32_bf16 v[108:111], v[148:151], v[180:183], v[108:111]
	v_mfma_f32_16x16x32_bf16 v[96:99], v[136:139], v[188:191], v[96:99]
	v_mfma_f32_16x16x32_bf16 v[92:95], v[148:151], v[188:191], v[92:95]
	v_mfma_f32_16x16x32_bf16 v[80:83], v[136:139], v[216:219], v[80:83]
	v_mfma_f32_16x16x32_bf16 v[76:79], v[148:151], v[216:219], v[76:79]
	s_setprio 0
	s_setprio 1
	v_mfma_f32_16x16x32_bf16 v[120:123], v[152:155], v[168:171], v[120:123]
	v_mfma_f32_16x16x32_bf16 v[116:119], v[160:163], v[168:171], v[116:119]
	v_mfma_f32_16x16x32_bf16 v[104:107], v[152:155], v[176:179], v[104:107]
	v_mfma_f32_16x16x32_bf16 v[100:103], v[160:163], v[176:179], v[100:103]
	v_mfma_f32_16x16x32_bf16 v[88:91], v[152:155], v[184:187], v[88:91]
	v_mfma_f32_16x16x32_bf16 v[84:87], v[160:163], v[184:187], v[84:87]
	v_mfma_f32_16x16x32_bf16 v[72:75], v[152:155], v[212:215], v[72:75]
	v_mfma_f32_16x16x32_bf16 v[68:71], v[160:163], v[212:215], v[68:71]
	v_mfma_f32_16x16x32_bf16 v[120:123], v[156:159], v[172:175], v[120:123]
	v_mfma_f32_16x16x32_bf16 v[116:119], v[164:167], v[172:175], v[116:119]
	v_mfma_f32_16x16x32_bf16 v[104:107], v[156:159], v[180:183], v[104:107]
	v_mfma_f32_16x16x32_bf16 v[100:103], v[164:167], v[180:183], v[100:103]
	v_mfma_f32_16x16x32_bf16 v[88:91], v[156:159], v[188:191], v[88:91]
	v_mfma_f32_16x16x32_bf16 v[84:87], v[164:167], v[188:191], v[84:87]
	v_mfma_f32_16x16x32_bf16 v[72:75], v[156:159], v[216:219], v[72:75]
	v_mfma_f32_16x16x32_bf16 v[68:71], v[164:167], v[216:219], v[68:71]
	s_setprio 0
	s_barrier
	s_add_i32 s4, s4, s51
	v_lshl_add_u64 v[194:195], s[38:39], 0, v[204:205]
	s_mov_b32 m0, s4
	ds_read_b128 v[168:171], v246 offset:16384
	ds_read_b128 v[172:175], v246 offset:17408
	ds_read_b128 v[176:179], v246 offset:18432
	ds_read_b128 v[180:183], v246 offset:19456
	ds_read_b128 v[184:187], v246 offset:20480
	ds_read_b128 v[188:191], v246 offset:21504
	ds_read_b128 v[212:215], v246 offset:22528
	ds_read_b128 v[216:219], v246 offset:23552
	global_load_lds_dwordx4 v[194:195], off
	s_add_i32 m0, s4, 0x2000
	s_add_u32 vcc_lo, s38, 0x40000
	v_lshl_add_u64 v[198:199], s[38:39], 0, v[192:193]
	s_addc_u32 vcc_hi, s39, 0
	s_add_i32 s4, s5, s51
	global_load_lds_dwordx4 v[198:199], off
	s_mov_b32 m0, s4
	s_nop 0
	global_load_lds_dwordx4 v204, vcc
	s_add_i32 m0, s4, 0x2000
	s_nop 0
	global_load_lds_dwordx4 v192, vcc
	s_mov_b32 m0, s55
	s_nop 0
	global_load_lds_dwordx4 v206, s[40:41]
	s_mov_b32 m0, s56
	s_nop 0
	global_load_lds_dwordx4 v202, s[40:41]
	s_waitcnt vmcnt(8)
	s_waitcnt lgkmcnt(0)
	s_barrier
	s_setprio 1
	s_waitcnt lgkmcnt(0)
	v_mfma_f32_16x16x32_bf16 v[64:67], v[132:135], v[168:171], v[64:67]
	v_mfma_f32_16x16x32_bf16 v[60:63], v[144:147], v[168:171], v[60:63]
	v_mfma_f32_16x16x32_bf16 v[48:51], v[132:135], v[176:179], v[48:51]
	v_mfma_f32_16x16x32_bf16 v[44:47], v[144:147], v[176:179], v[44:47]
	v_mfma_f32_16x16x32_bf16 v[32:35], v[132:135], v[184:187], v[32:35]
	v_mfma_f32_16x16x32_bf16 v[28:31], v[144:147], v[184:187], v[28:31]
	v_mfma_f32_16x16x32_bf16 v[16:19], v[132:135], v[212:215], v[16:19]
	v_mfma_f32_16x16x32_bf16 v[12:15], v[144:147], v[212:215], v[12:15]
	v_mfma_f32_16x16x32_bf16 v[64:67], v[136:139], v[172:175], v[64:67]
	v_mfma_f32_16x16x32_bf16 v[60:63], v[148:151], v[172:175], v[60:63]
	v_mfma_f32_16x16x32_bf16 v[48:51], v[136:139], v[180:183], v[48:51]
	v_mfma_f32_16x16x32_bf16 v[44:47], v[148:151], v[180:183], v[44:47]
	v_mfma_f32_16x16x32_bf16 v[32:35], v[136:139], v[188:191], v[32:35]
	v_mfma_f32_16x16x32_bf16 v[28:31], v[148:151], v[188:191], v[28:31]
	v_mfma_f32_16x16x32_bf16 v[16:19], v[136:139], v[216:219], v[16:19]
	v_mfma_f32_16x16x32_bf16 v[12:15], v[148:151], v[216:219], v[12:15]
	s_setprio 0
	s_setprio 1
	v_mfma_f32_16x16x32_bf16 v[56:59], v[152:155], v[168:171], v[56:59]
	v_mfma_f32_16x16x32_bf16 v[52:55], v[160:163], v[168:171], v[52:55]
	v_mfma_f32_16x16x32_bf16 v[40:43], v[152:155], v[176:179], v[40:43]
	v_mfma_f32_16x16x32_bf16 v[36:39], v[160:163], v[176:179], v[36:39]
	v_mfma_f32_16x16x32_bf16 v[24:27], v[152:155], v[184:187], v[24:27]
	v_mfma_f32_16x16x32_bf16 v[20:23], v[160:163], v[184:187], v[20:23]
	v_mfma_f32_16x16x32_bf16 v[8:11], v[152:155], v[212:215], v[8:11]
	v_mfma_f32_16x16x32_bf16 v[2:5], v[160:163], v[212:215], v[4:7]
	v_mfma_f32_16x16x32_bf16 v[56:59], v[156:159], v[172:175], v[56:59]
	v_mfma_f32_16x16x32_bf16 v[52:55], v[164:167], v[172:175], v[52:55]
	v_mfma_f32_16x16x32_bf16 v[40:43], v[156:159], v[180:183], v[40:43]
	v_mfma_f32_16x16x32_bf16 v[36:39], v[164:167], v[180:183], v[36:39]
	v_mfma_f32_16x16x32_bf16 v[24:27], v[156:159], v[188:191], v[24:27]
	v_mfma_f32_16x16x32_bf16 v[20:23], v[164:167], v[188:191], v[20:23]
	v_mfma_f32_16x16x32_bf16 v[8:11], v[156:159], v[216:219], v[8:11]
	v_mfma_f32_16x16x32_bf16 v[2:5], v[164:167], v[216:219], v[2:5]
	s_setprio 0
	s_barrier
	s_add_i32 s4, 0, 0x18000
	v_add_u32_e32 v0, s4, v244
	s_add_i32 s5, 0, 0x1c000
	ds_read_b128 v[132:135], v0
	ds_read_b128 v[136:139], v0 offset:1024
	ds_read_b128 v[144:147], v0 offset:2048
	ds_read_b128 v[148:151], v0 offset:3072
	v_add_u32_e32 v0, s5, v244
	ds_read_b128 v[152:155], v0
	ds_read_b128 v[156:159], v0 offset:1024
	ds_read_b128 v[160:163], v0 offset:2048
	ds_read_b128 v[164:167], v0 offset:3072
	s_add_u32 s40, s40, 0xe0000
	s_addc_u32 s41, s41, 0
	s_mov_b32 m0, s57
	ds_read_b128 v[168:171], v246 offset:32768
	ds_read_b128 v[172:175], v246 offset:33792
	ds_read_b128 v[176:179], v246 offset:34816
	ds_read_b128 v[180:183], v246 offset:35840
	ds_read_b128 v[184:187], v246 offset:36864
	ds_read_b128 v[188:191], v246 offset:37888
	ds_read_b128 v[212:215], v246 offset:38912
	ds_read_b128 v[216:219], v246 offset:39936
	global_load_lds_dwordx4 v206, s[40:41]
	s_mov_b32 m0, s58
	s_nop 0
	global_load_lds_dwordx4 v202, s[40:41]
	s_waitcnt vmcnt(8)
	s_waitcnt lgkmcnt(0)
	s_barrier
	s_setprio 1
	s_waitcnt lgkmcnt(0)
	v_mfma_f32_16x16x32_bf16 v[128:131], v[132:135], v[168:171], v[128:131]
	v_mfma_f32_16x16x32_bf16 v[124:127], v[144:147], v[168:171], v[124:127]
	v_mfma_f32_16x16x32_bf16 v[112:115], v[132:135], v[176:179], v[112:115]
	v_mfma_f32_16x16x32_bf16 v[108:111], v[144:147], v[176:179], v[108:111]
	v_mfma_f32_16x16x32_bf16 v[96:99], v[132:135], v[184:187], v[96:99]
	v_mfma_f32_16x16x32_bf16 v[92:95], v[144:147], v[184:187], v[92:95]
	v_mfma_f32_16x16x32_bf16 v[80:83], v[132:135], v[212:215], v[80:83]
	v_mfma_f32_16x16x32_bf16 v[76:79], v[144:147], v[212:215], v[76:79]
	v_mfma_f32_16x16x32_bf16 v[128:131], v[136:139], v[172:175], v[128:131]
	v_mfma_f32_16x16x32_bf16 v[124:127], v[148:151], v[172:175], v[124:127]
	v_mfma_f32_16x16x32_bf16 v[112:115], v[136:139], v[180:183], v[112:115]
	v_mfma_f32_16x16x32_bf16 v[108:111], v[148:151], v[180:183], v[108:111]
	v_mfma_f32_16x16x32_bf16 v[96:99], v[136:139], v[188:191], v[96:99]
	v_mfma_f32_16x16x32_bf16 v[92:95], v[148:151], v[188:191], v[92:95]
	v_mfma_f32_16x16x32_bf16 v[80:83], v[136:139], v[216:219], v[80:83]
	v_mfma_f32_16x16x32_bf16 v[76:79], v[148:151], v[216:219], v[76:79]
	s_setprio 0
	s_setprio 1
	v_mfma_f32_16x16x32_bf16 v[120:123], v[152:155], v[168:171], v[120:123]
	v_mfma_f32_16x16x32_bf16 v[116:119], v[160:163], v[168:171], v[116:119]
	v_mfma_f32_16x16x32_bf16 v[104:107], v[152:155], v[176:179], v[104:107]
	v_mfma_f32_16x16x32_bf16 v[100:103], v[160:163], v[176:179], v[100:103]
	v_mfma_f32_16x16x32_bf16 v[88:91], v[152:155], v[184:187], v[88:91]
	v_mfma_f32_16x16x32_bf16 v[84:87], v[160:163], v[184:187], v[84:87]
	v_mfma_f32_16x16x32_bf16 v[72:75], v[152:155], v[212:215], v[72:75]
	v_mfma_f32_16x16x32_bf16 v[68:71], v[160:163], v[212:215], v[68:71]
	v_mfma_f32_16x16x32_bf16 v[120:123], v[156:159], v[172:175], v[120:123]
	v_mfma_f32_16x16x32_bf16 v[116:119], v[164:167], v[172:175], v[116:119]
	v_mfma_f32_16x16x32_bf16 v[104:107], v[156:159], v[180:183], v[104:107]
	v_mfma_f32_16x16x32_bf16 v[100:103], v[164:167], v[180:183], v[100:103]
	v_mfma_f32_16x16x32_bf16 v[88:91], v[156:159], v[188:191], v[88:91]
	v_mfma_f32_16x16x32_bf16 v[84:87], v[164:167], v[188:191], v[84:87]
	v_mfma_f32_16x16x32_bf16 v[72:75], v[156:159], v[216:219], v[72:75]
	v_mfma_f32_16x16x32_bf16 v[68:71], v[164:167], v[216:219], v[68:71]
	s_setprio 0
	s_barrier
	s_add_i32 s4, s4, s51
	v_lshl_add_u64 v[6:7], v[194:195], 0, s[90:91]
	s_mov_b32 m0, s4
	ds_read_b128 v[168:171], v246 offset:49152
	ds_read_b128 v[172:175], v246 offset:50176
	ds_read_b128 v[176:179], v246 offset:51200
	ds_read_b128 v[180:183], v246 offset:52224
	ds_read_b128 v[184:187], v246 offset:53248
	ds_read_b128 v[188:191], v246 offset:54272
	ds_read_b128 v[212:215], v246 offset:55296
	ds_read_b128 v[216:219], v246 offset:56320
	global_load_lds_dwordx4 v[6:7], off
	s_add_i32 m0, s4, 0x2000
	s_add_u32 s38, s38, 0x40080
	v_lshl_add_u64 v[6:7], v[198:199], 0, s[90:91]
	s_addc_u32 s39, s39, 0
	s_add_i32 s4, s5, s51
	global_load_lds_dwordx4 v[6:7], off
	s_mov_b32 m0, s4
	s_nop 0
	global_load_lds_dwordx4 v204, s[38:39]
	s_add_i32 m0, s4, 0x2000
	s_nop 0
	global_load_lds_dwordx4 v192, s[38:39]
	s_mov_b32 m0, s68
	s_nop 0
	global_load_lds_dwordx4 v206, s[10:11]
	s_mov_b32 m0, s69
	s_nop 0
	global_load_lds_dwordx4 v202, s[10:11]
	s_waitcnt vmcnt(8)
	s_waitcnt lgkmcnt(0)
	s_barrier
	s_setprio 1
	s_waitcnt lgkmcnt(0)
	v_mfma_f32_16x16x32_bf16 v[64:67], v[132:135], v[168:171], v[64:67]
	v_mfma_f32_16x16x32_bf16 v[60:63], v[144:147], v[168:171], v[60:63]
	v_mfma_f32_16x16x32_bf16 v[48:51], v[132:135], v[176:179], v[48:51]
	v_mfma_f32_16x16x32_bf16 v[44:47], v[144:147], v[176:179], v[44:47]
	v_mfma_f32_16x16x32_bf16 v[32:35], v[132:135], v[184:187], v[32:35]
	v_mfma_f32_16x16x32_bf16 v[28:31], v[144:147], v[184:187], v[28:31]
	v_mfma_f32_16x16x32_bf16 v[16:19], v[132:135], v[212:215], v[16:19]
	v_mfma_f32_16x16x32_bf16 v[12:15], v[144:147], v[212:215], v[12:15]
	v_mfma_f32_16x16x32_bf16 v[64:67], v[136:139], v[172:175], v[64:67]
	v_mfma_f32_16x16x32_bf16 v[60:63], v[148:151], v[172:175], v[60:63]
	v_mfma_f32_16x16x32_bf16 v[48:51], v[136:139], v[180:183], v[48:51]
	v_mfma_f32_16x16x32_bf16 v[44:47], v[148:151], v[180:183], v[44:47]
	v_mfma_f32_16x16x32_bf16 v[32:35], v[136:139], v[188:191], v[32:35]
	v_mfma_f32_16x16x32_bf16 v[28:31], v[148:151], v[188:191], v[28:31]
	v_mfma_f32_16x16x32_bf16 v[16:19], v[136:139], v[216:219], v[16:19]
	v_mfma_f32_16x16x32_bf16 v[12:15], v[148:151], v[216:219], v[12:15]
	s_setprio 0
	s_setprio 1
	v_mfma_f32_16x16x32_bf16 v[56:59], v[152:155], v[168:171], v[56:59]
	v_mfma_f32_16x16x32_bf16 v[52:55], v[160:163], v[168:171], v[52:55]
	v_mfma_f32_16x16x32_bf16 v[40:43], v[152:155], v[176:179], v[40:43]
	v_mfma_f32_16x16x32_bf16 v[36:39], v[160:163], v[176:179], v[36:39]
	v_mfma_f32_16x16x32_bf16 v[24:27], v[152:155], v[184:187], v[24:27]
	v_mfma_f32_16x16x32_bf16 v[20:23], v[160:163], v[184:187], v[20:23]
	v_mfma_f32_16x16x32_bf16 v[6:9], v[152:155], v[212:215], v[8:11]
	v_mfma_f32_16x16x32_bf16 v[2:5], v[160:163], v[212:215], v[2:5]
	v_mfma_f32_16x16x32_bf16 v[56:59], v[156:159], v[172:175], v[56:59]
	v_mfma_f32_16x16x32_bf16 v[52:55], v[164:167], v[172:175], v[52:55]
	v_mfma_f32_16x16x32_bf16 v[40:43], v[156:159], v[180:183], v[40:43]
	v_mfma_f32_16x16x32_bf16 v[36:39], v[164:167], v[180:183], v[36:39]
	v_mfma_f32_16x16x32_bf16 v[24:27], v[156:159], v[188:191], v[24:27]
	v_mfma_f32_16x16x32_bf16 v[20:23], v[164:167], v[188:191], v[20:23]
	v_mfma_f32_16x16x32_bf16 v[8:11], v[156:159], v[216:219], v[6:9]
	v_mfma_f32_16x16x32_bf16 v[4:7], v[164:167], v[216:219], v[2:5]
	s_setprio 0
	s_barrier
	s_add_u32 s36, s36, 0x100
	s_addc_u32 s37, s37, 0
	s_cmp_gt_u32 s78, 13
	s_cbranch_scc1 .LBB0_544

.LBB0_585:
	s_add_i32 s78, s78, 2
	s_cmp_gt_u32 s78, 7
	s_cselect_b32 s85, 0xffffec00, 0
	s_cselect_b32 s87, -1, 0
	s_cmp_gt_u32 s78, 5
	s_cselect_b32 s35, 0xffffec00, 0
	s_cselect_b32 s34, -1, 0
	s_add_u32 s35, s35, s12
	s_addc_u32 s34, s34, s13
	s_add_u32 s35, s30, s35
	s_addc_u32 s34, s31, s34
	s_add_u32 s35, s35, 0x100
	s_addc_u32 s34, s34, 0
	s_add_u32 s36, s75, s12
	s_addc_u32 s37, s76, s13
	s_cmp_gt_u32 s78, 4
	s_cselect_b32 s39, 0xffffec00, 0
	s_cselect_b32 s38, -1, 0
	s_add_u32 s39, s39, s12
	s_addc_u32 s38, s38, s13
	s_add_u32 s39, s30, s39
	s_addc_u32 s38, s31, s38
	s_add_u32 s86, s39, 0x180
	s_addc_u32 vcc_lo, s38, 0
	s_cmpk_eq_i32 s12, 0x700
	s_cselect_b32 s39, s27, s34
	s_cselect_b32 s38, s26, s35
	s_cselect_b32 s37, s25, s37
	s_cselect_b32 s36, s72, s36
	s_cselect_b32 s35, s74, vcc_lo
	s_cselect_b32 s34, s73, s86
	s_add_i32 vcc_lo, 0, 0x10000
	v_add_u32_e32 v0, vcc_lo, v243
	s_add_i32 vcc_hi, 0, 0x14000
	ds_read_b128 v[128:131], v0
	ds_read_b128 v[132:135], v0 offset:1024
	ds_read_b128 v[136:139], v0 offset:2048
	ds_read_b128 v[140:143], v0 offset:3072
	v_add_u32_e32 v0, vcc_hi, v243
	ds_read_b128 v[152:155], v0
	ds_read_b128 v[156:159], v0 offset:1024
	ds_read_b128 v[160:163], v0 offset:2048
	ds_read_b128 v[164:167], v0 offset:3072
	s_add_u32 s86, s85, s12
	s_addc_u32 s87, s87, s13
	v_lshl_add_u64 v[2:3], v[124:125], 0, s[86:87]
	s_add_i32 m0, s41, 0xc000
	ds_read_b128 v[168:171], v245
	ds_read_b128 v[172:175], v245 offset:1024
	ds_read_b128 v[176:179], v245 offset:2048
	ds_read_b128 v[180:183], v245 offset:3072
	ds_read_b128 v[184:187], v245 offset:4096
	ds_read_b128 v[188:191], v245 offset:5120
	ds_read_b128 v[212:215], v245 offset:6144
	ds_read_b128 v[216:219], v245 offset:7168
	global_load_lds_dwordx4 v[2:3], off
	v_lshl_add_u64 v[2:3], v[126:127], 0, s[86:87]
	s_add_i32 m0, s41, 0xe000
	s_nop 0
	global_load_lds_dwordx4 v[2:3], off
	s_waitcnt vmcnt(8)
	s_waitcnt lgkmcnt(0)
	s_barrier
	s_setprio 1
	s_waitcnt lgkmcnt(0)
	v_mfma_f32_16x16x32_bf16 v[148:151], v[128:131], v[168:171], v[148:151]
	v_mfma_f32_16x16x32_bf16 v[144:147], v[136:139], v[168:171], v[144:147]
	v_mfma_f32_16x16x32_bf16 v[112:115], v[128:131], v[176:179], v[112:115]
	v_mfma_f32_16x16x32_bf16 v[108:111], v[136:139], v[176:179], v[108:111]
	v_mfma_f32_16x16x32_bf16 v[96:99], v[128:131], v[184:187], v[96:99]
	v_mfma_f32_16x16x32_bf16 v[92:95], v[136:139], v[184:187], v[92:95]
	v_mfma_f32_16x16x32_bf16 v[80:83], v[128:131], v[212:215], v[80:83]
	v_mfma_f32_16x16x32_bf16 v[76:79], v[136:139], v[212:215], v[76:79]
	v_mfma_f32_16x16x32_bf16 v[148:151], v[132:135], v[172:175], v[148:151]
	v_mfma_f32_16x16x32_bf16 v[144:147], v[140:143], v[172:175], v[144:147]
	v_mfma_f32_16x16x32_bf16 v[112:115], v[132:135], v[180:183], v[112:115]
	v_mfma_f32_16x16x32_bf16 v[108:111], v[140:143], v[180:183], v[108:111]
	v_mfma_f32_16x16x32_bf16 v[96:99], v[132:135], v[188:191], v[96:99]
	v_mfma_f32_16x16x32_bf16 v[92:95], v[140:143], v[188:191], v[92:95]
	v_mfma_f32_16x16x32_bf16 v[80:83], v[132:135], v[216:219], v[80:83]
	v_mfma_f32_16x16x32_bf16 v[76:79], v[140:143], v[216:219], v[76:79]
	s_setprio 0
	s_setprio 1
	v_mfma_f32_16x16x32_bf16 v[120:123], v[152:155], v[168:171], v[120:123]
	v_mfma_f32_16x16x32_bf16 v[116:119], v[160:163], v[168:171], v[116:119]
	v_mfma_f32_16x16x32_bf16 v[104:107], v[152:155], v[176:179], v[104:107]
	v_mfma_f32_16x16x32_bf16 v[100:103], v[160:163], v[176:179], v[100:103]
	v_mfma_f32_16x16x32_bf16 v[88:91], v[152:155], v[184:187], v[88:91]
	v_mfma_f32_16x16x32_bf16 v[84:87], v[160:163], v[184:187], v[84:87]
	v_mfma_f32_16x16x32_bf16 v[72:75], v[152:155], v[212:215], v[72:75]
	v_mfma_f32_16x16x32_bf16 v[68:71], v[160:163], v[212:215], v[68:71]
	v_mfma_f32_16x16x32_bf16 v[120:123], v[156:159], v[172:175], v[120:123]
	v_mfma_f32_16x16x32_bf16 v[116:119], v[164:167], v[172:175], v[116:119]
	v_mfma_f32_16x16x32_bf16 v[104:107], v[156:159], v[180:183], v[104:107]
	v_mfma_f32_16x16x32_bf16 v[100:103], v[164:167], v[180:183], v[100:103]
	v_mfma_f32_16x16x32_bf16 v[88:91], v[156:159], v[188:191], v[88:91]
	v_mfma_f32_16x16x32_bf16 v[84:87], v[164:167], v[188:191], v[84:87]
	v_mfma_f32_16x16x32_bf16 v[72:75], v[156:159], v[216:219], v[72:75]
	v_mfma_f32_16x16x32_bf16 v[68:71], v[164:167], v[216:219], v[68:71]
	s_setprio 0
	s_barrier
	s_add_i32 s85, vcc_lo, s40
	v_lshl_add_u64 v[194:195], s[36:37], 0, v[204:205]
	s_mov_b32 m0, s85
	ds_read_b128 v[168:171], v245 offset:16384
	ds_read_b128 v[172:175], v245 offset:17408
	ds_read_b128 v[176:179], v245 offset:18432
	ds_read_b128 v[180:183], v245 offset:19456
	ds_read_b128 v[184:187], v245 offset:20480
	ds_read_b128 v[188:191], v245 offset:21504
	ds_read_b128 v[212:215], v245 offset:22528
	ds_read_b128 v[216:219], v245 offset:23552
	global_load_lds_dwordx4 v[194:195], off
	s_add_i32 m0, s85, 0x2000
	s_add_u32 s86, s36, 0x40000
	v_lshl_add_u64 v[198:199], s[36:37], 0, v[192:193]
	s_addc_u32 s87, s37, 0
	s_add_i32 s85, vcc_hi, s40
	global_load_lds_dwordx4 v[198:199], off
	s_mov_b32 m0, s85
	s_nop 0
	global_load_lds_dwordx4 v204, s[86:87]
	s_add_i32 m0, s85, 0x2000
	s_nop 0
	global_load_lds_dwordx4 v192, s[86:87]
	s_mov_b32 m0, s41
	s_nop 0
	global_load_lds_dwordx4 v206, s[38:39]
	s_mov_b32 m0, s51
	s_nop 0
	global_load_lds_dwordx4 v202, s[38:39]
	s_waitcnt vmcnt(8)
	s_waitcnt lgkmcnt(0)
	s_barrier
	s_setprio 1
	s_waitcnt lgkmcnt(0)
	v_mfma_f32_16x16x32_bf16 v[64:67], v[128:131], v[168:171], v[64:67]
	v_mfma_f32_16x16x32_bf16 v[60:63], v[136:139], v[168:171], v[60:63]
	v_mfma_f32_16x16x32_bf16 v[48:51], v[128:131], v[176:179], v[48:51]
	v_mfma_f32_16x16x32_bf16 v[44:47], v[136:139], v[176:179], v[44:47]
	v_mfma_f32_16x16x32_bf16 v[32:35], v[128:131], v[184:187], v[32:35]
	v_mfma_f32_16x16x32_bf16 v[28:31], v[136:139], v[184:187], v[28:31]
	v_mfma_f32_16x16x32_bf16 v[16:19], v[128:131], v[212:215], v[16:19]
	v_mfma_f32_16x16x32_bf16 v[12:15], v[136:139], v[212:215], v[12:15]
	v_mfma_f32_16x16x32_bf16 v[64:67], v[132:135], v[172:175], v[64:67]
	v_mfma_f32_16x16x32_bf16 v[60:63], v[140:143], v[172:175], v[60:63]
	v_mfma_f32_16x16x32_bf16 v[48:51], v[132:135], v[180:183], v[48:51]
	v_mfma_f32_16x16x32_bf16 v[44:47], v[140:143], v[180:183], v[44:47]
	v_mfma_f32_16x16x32_bf16 v[32:35], v[132:135], v[188:191], v[32:35]
	v_mfma_f32_16x16x32_bf16 v[28:31], v[140:143], v[188:191], v[28:31]
	v_mfma_f32_16x16x32_bf16 v[16:19], v[132:135], v[216:219], v[16:19]
	v_mfma_f32_16x16x32_bf16 v[12:15], v[140:143], v[216:219], v[12:15]
	s_setprio 0
	s_setprio 1
	v_mfma_f32_16x16x32_bf16 v[56:59], v[152:155], v[168:171], v[56:59]
	v_mfma_f32_16x16x32_bf16 v[52:55], v[160:163], v[168:171], v[52:55]
	v_mfma_f32_16x16x32_bf16 v[40:43], v[152:155], v[176:179], v[40:43]
	v_mfma_f32_16x16x32_bf16 v[36:39], v[160:163], v[176:179], v[36:39]
	v_mfma_f32_16x16x32_bf16 v[24:27], v[152:155], v[184:187], v[24:27]
	v_mfma_f32_16x16x32_bf16 v[20:23], v[160:163], v[184:187], v[20:23]
	v_mfma_f32_16x16x32_bf16 v[8:11], v[152:155], v[212:215], v[8:11]
	v_mfma_f32_16x16x32_bf16 v[2:5], v[160:163], v[212:215], v[4:7]
	v_mfma_f32_16x16x32_bf16 v[56:59], v[156:159], v[172:175], v[56:59]
	v_mfma_f32_16x16x32_bf16 v[52:55], v[164:167], v[172:175], v[52:55]
	v_mfma_f32_16x16x32_bf16 v[40:43], v[156:159], v[180:183], v[40:43]
	v_mfma_f32_16x16x32_bf16 v[36:39], v[164:167], v[180:183], v[36:39]
	v_mfma_f32_16x16x32_bf16 v[24:27], v[156:159], v[188:191], v[24:27]
	v_mfma_f32_16x16x32_bf16 v[20:23], v[164:167], v[188:191], v[20:23]
	v_mfma_f32_16x16x32_bf16 v[8:11], v[156:159], v[216:219], v[8:11]
	v_mfma_f32_16x16x32_bf16 v[2:5], v[164:167], v[216:219], v[2:5]
	s_setprio 0
	s_barrier
	s_add_i32 s85, 0, 0x18000
	v_add_u32_e32 v0, s85, v243
	s_add_i32 s86, 0, 0x1c000
	ds_read_b128 v[128:131], v0
	ds_read_b128 v[132:135], v0 offset:1024
	ds_read_b128 v[136:139], v0 offset:2048
	ds_read_b128 v[140:143], v0 offset:3072
	v_add_u32_e32 v0, s86, v243
	ds_read_b128 v[152:155], v0
	ds_read_b128 v[156:159], v0 offset:1024
	ds_read_b128 v[160:163], v0 offset:2048
	ds_read_b128 v[164:167], v0 offset:3072
	s_add_u32 s38, s38, 0xe0000
	s_addc_u32 s39, s39, 0
	s_mov_b32 m0, s55
	ds_read_b128 v[168:171], v245 offset:32768
	ds_read_b128 v[172:175], v245 offset:33792
	ds_read_b128 v[176:179], v245 offset:34816
	ds_read_b128 v[180:183], v245 offset:35840
	ds_read_b128 v[184:187], v245 offset:36864
	ds_read_b128 v[188:191], v245 offset:37888
	ds_read_b128 v[212:215], v245 offset:38912
	ds_read_b128 v[216:219], v245 offset:39936
	global_load_lds_dwordx4 v206, s[38:39]
	s_mov_b32 m0, s56
	s_nop 0
	global_load_lds_dwordx4 v202, s[38:39]
	s_waitcnt vmcnt(8)
	s_waitcnt lgkmcnt(0)
	s_barrier
	s_setprio 1
	s_waitcnt lgkmcnt(0)
	v_mfma_f32_16x16x32_bf16 v[148:151], v[128:131], v[168:171], v[148:151]
	v_mfma_f32_16x16x32_bf16 v[144:147], v[136:139], v[168:171], v[144:147]
	v_mfma_f32_16x16x32_bf16 v[112:115], v[128:131], v[176:179], v[112:115]
	v_mfma_f32_16x16x32_bf16 v[108:111], v[136:139], v[176:179], v[108:111]
	v_mfma_f32_16x16x32_bf16 v[96:99], v[128:131], v[184:187], v[96:99]
	v_mfma_f32_16x16x32_bf16 v[92:95], v[136:139], v[184:187], v[92:95]
	v_mfma_f32_16x16x32_bf16 v[80:83], v[128:131], v[212:215], v[80:83]
	v_mfma_f32_16x16x32_bf16 v[76:79], v[136:139], v[212:215], v[76:79]
	v_mfma_f32_16x16x32_bf16 v[148:151], v[132:135], v[172:175], v[148:151]
	v_mfma_f32_16x16x32_bf16 v[144:147], v[140:143], v[172:175], v[144:147]
	v_mfma_f32_16x16x32_bf16 v[112:115], v[132:135], v[180:183], v[112:115]
	v_mfma_f32_16x16x32_bf16 v[108:111], v[140:143], v[180:183], v[108:111]
	v_mfma_f32_16x16x32_bf16 v[96:99], v[132:135], v[188:191], v[96:99]
	v_mfma_f32_16x16x32_bf16 v[92:95], v[140:143], v[188:191], v[92:95]
	v_mfma_f32_16x16x32_bf16 v[80:83], v[132:135], v[216:219], v[80:83]
	v_mfma_f32_16x16x32_bf16 v[76:79], v[140:143], v[216:219], v[76:79]
	s_setprio 0
	s_setprio 1
	v_mfma_f32_16x16x32_bf16 v[120:123], v[152:155], v[168:171], v[120:123]
	v_mfma_f32_16x16x32_bf16 v[116:119], v[160:163], v[168:171], v[116:119]
	v_mfma_f32_16x16x32_bf16 v[104:107], v[152:155], v[176:179], v[104:107]
	v_mfma_f32_16x16x32_bf16 v[100:103], v[160:163], v[176:179], v[100:103]
	v_mfma_f32_16x16x32_bf16 v[88:91], v[152:155], v[184:187], v[88:91]
	v_mfma_f32_16x16x32_bf16 v[84:87], v[160:163], v[184:187], v[84:87]
	v_mfma_f32_16x16x32_bf16 v[72:75], v[152:155], v[212:215], v[72:75]
	v_mfma_f32_16x16x32_bf16 v[68:71], v[160:163], v[212:215], v[68:71]
	v_mfma_f32_16x16x32_bf16 v[120:123], v[156:159], v[172:175], v[120:123]
	v_mfma_f32_16x16x32_bf16 v[116:119], v[164:167], v[172:175], v[116:119]
	v_mfma_f32_16x16x32_bf16 v[104:107], v[156:159], v[180:183], v[104:107]
	v_mfma_f32_16x16x32_bf16 v[100:103], v[164:167], v[180:183], v[100:103]
	v_mfma_f32_16x16x32_bf16 v[88:91], v[156:159], v[188:191], v[88:91]
	v_mfma_f32_16x16x32_bf16 v[84:87], v[164:167], v[188:191], v[84:87]
	v_mfma_f32_16x16x32_bf16 v[72:75], v[156:159], v[216:219], v[72:75]
	v_mfma_f32_16x16x32_bf16 v[68:71], v[164:167], v[216:219], v[68:71]
	s_setprio 0
	s_barrier
	s_add_i32 s38, s85, s40
	v_lshl_add_u64 v[6:7], v[194:195], 0, s[90:91]
	s_mov_b32 m0, s38
	ds_read_b128 v[168:171], v245 offset:49152
	ds_read_b128 v[172:175], v245 offset:50176
	ds_read_b128 v[176:179], v245 offset:51200
	ds_read_b128 v[180:183], v245 offset:52224
	ds_read_b128 v[184:187], v245 offset:53248
	ds_read_b128 v[188:191], v245 offset:54272
	ds_read_b128 v[212:215], v245 offset:55296
	ds_read_b128 v[216:219], v245 offset:56320
	global_load_lds_dwordx4 v[6:7], off
	s_add_i32 m0, s38, 0x2000
	s_add_u32 s36, s36, 0x40080
	v_lshl_add_u64 v[6:7], v[198:199], 0, s[90:91]
	s_addc_u32 s37, s37, 0
	s_add_i32 s38, s86, s40
	global_load_lds_dwordx4 v[6:7], off
	s_mov_b32 m0, s38
	s_nop 0
	global_load_lds_dwordx4 v204, s[36:37]
	s_add_i32 m0, s38, 0x2000
	s_nop 0
	global_load_lds_dwordx4 v192, s[36:37]
	s_mov_b32 m0, s57
	s_nop 0
	global_load_lds_dwordx4 v206, s[34:35]
	s_mov_b32 m0, s58
	s_nop 0
	global_load_lds_dwordx4 v202, s[34:35]
	s_waitcnt vmcnt(8)
	s_waitcnt lgkmcnt(0)
	s_barrier
	s_setprio 1
	s_waitcnt lgkmcnt(0)
	v_mfma_f32_16x16x32_bf16 v[64:67], v[128:131], v[168:171], v[64:67]
	v_mfma_f32_16x16x32_bf16 v[60:63], v[136:139], v[168:171], v[60:63]
	v_mfma_f32_16x16x32_bf16 v[48:51], v[128:131], v[176:179], v[48:51]
	v_mfma_f32_16x16x32_bf16 v[44:47], v[136:139], v[176:179], v[44:47]
	v_mfma_f32_16x16x32_bf16 v[32:35], v[128:131], v[184:187], v[32:35]
	v_mfma_f32_16x16x32_bf16 v[28:31], v[136:139], v[184:187], v[28:31]
	v_mfma_f32_16x16x32_bf16 v[16:19], v[128:131], v[212:215], v[16:19]
	v_mfma_f32_16x16x32_bf16 v[12:15], v[136:139], v[212:215], v[12:15]
	v_mfma_f32_16x16x32_bf16 v[64:67], v[132:135], v[172:175], v[64:67]
	v_mfma_f32_16x16x32_bf16 v[60:63], v[140:143], v[172:175], v[60:63]
	v_mfma_f32_16x16x32_bf16 v[48:51], v[132:135], v[180:183], v[48:51]
	v_mfma_f32_16x16x32_bf16 v[44:47], v[140:143], v[180:183], v[44:47]
	v_mfma_f32_16x16x32_bf16 v[32:35], v[132:135], v[188:191], v[32:35]
	v_mfma_f32_16x16x32_bf16 v[28:31], v[140:143], v[188:191], v[28:31]
	v_mfma_f32_16x16x32_bf16 v[16:19], v[132:135], v[216:219], v[16:19]
	v_mfma_f32_16x16x32_bf16 v[12:15], v[140:143], v[216:219], v[12:15]
	s_setprio 0
	s_setprio 1
	v_mfma_f32_16x16x32_bf16 v[56:59], v[152:155], v[168:171], v[56:59]
	v_mfma_f32_16x16x32_bf16 v[52:55], v[160:163], v[168:171], v[52:55]
	v_mfma_f32_16x16x32_bf16 v[40:43], v[152:155], v[176:179], v[40:43]
	v_mfma_f32_16x16x32_bf16 v[36:39], v[160:163], v[176:179], v[36:39]
	v_mfma_f32_16x16x32_bf16 v[24:27], v[152:155], v[184:187], v[24:27]
	v_mfma_f32_16x16x32_bf16 v[20:23], v[160:163], v[184:187], v[20:23]
	v_mfma_f32_16x16x32_bf16 v[6:9], v[152:155], v[212:215], v[8:11]
	v_mfma_f32_16x16x32_bf16 v[2:5], v[160:163], v[212:215], v[2:5]
	v_mfma_f32_16x16x32_bf16 v[56:59], v[156:159], v[172:175], v[56:59]
	v_mfma_f32_16x16x32_bf16 v[52:55], v[164:167], v[172:175], v[52:55]
	v_mfma_f32_16x16x32_bf16 v[40:43], v[156:159], v[180:183], v[40:43]
	v_mfma_f32_16x16x32_bf16 v[36:39], v[164:167], v[180:183], v[36:39]
	v_mfma_f32_16x16x32_bf16 v[24:27], v[156:159], v[188:191], v[24:27]
	v_mfma_f32_16x16x32_bf16 v[20:23], v[164:167], v[188:191], v[20:23]
	v_mfma_f32_16x16x32_bf16 v[8:11], v[156:159], v[216:219], v[6:9]
	v_mfma_f32_16x16x32_bf16 v[4:7], v[164:167], v[216:219], v[2:5]
	s_setprio 0
	s_barrier
	s_add_u32 s12, s12, 0x100
	s_addc_u32 s13, s13, 0
	s_cmp_gt_u32 s78, 13
	s_cbranch_scc1 .LBB0_588

.LBB0_675:
	s_add_u32 s4, s30, s34
	s_addc_u32 s5, s31, s35
	s_add_u32 s40, s4, 0x100
	s_addc_u32 s41, s5, 0
	s_add_u32 s38, s78, s34
	s_addc_u32 s39, s85, s35
	s_add_u32 s4, s4, 0x180
	s_addc_u32 s5, s5, 0
	s_add_i32 s87, 0, 0x10000
	s_add_i32 s65, 0, 0x14000
	v_add_u32_e32 v0, s87, v148
	ds_read_b128 v[150:153], v0
	ds_read_b128 v[154:157], v0 offset:1024
	ds_read_b128 v[158:161], v0 offset:2048
	ds_read_b128 v[162:165], v0 offset:3072
	v_add_u32_e32 v0, s65, v148
	ds_read_b128 v[166:169], v0
	ds_read_b128 v[170:173], v0 offset:1024
	ds_read_b128 v[174:177], v0 offset:2048
	ds_read_b128 v[178:181], v0 offset:3072
	s_cmpk_eq_i32 s34, 0x700
	s_cselect_b32 s37, s76, s5
	s_cselect_b32 s36, s75, s4
	s_cselect_b32 s39, s23, s39
	s_cselect_b32 s38, s74, s38
	s_cselect_b32 s41, s25, s41
	s_cselect_b32 s40, s73, s40
	v_lshl_add_u64 v[194:195], v[144:145], 0, s[34:35]
	s_add_i32 m0, s55, 0xc000
	ds_read_b128 v[182:185], v149
	ds_read_b128 v[186:189], v149 offset:1024
	ds_read_b128 v[190:193], v149 offset:2048
	ds_read_b128 v[202:205], v149 offset:3072
	ds_read_b128 v[206:209], v149 offset:4096
	ds_read_b128 v[210:213], v149 offset:5120
	ds_read_b128 v[214:217], v149 offset:6144
	ds_read_b128 v[218:221], v149 offset:7168
	global_load_lds_dwordx4 v[194:195], off
	v_lshl_add_u64 v[194:195], v[146:147], 0, s[34:35]
	s_add_i32 m0, s55, 0xe000
	s_nop 0
	global_load_lds_dwordx4 v[194:195], off
	s_waitcnt vmcnt(8)
	s_waitcnt lgkmcnt(0)
	s_barrier
	s_setprio 1
	s_waitcnt lgkmcnt(0)
	v_mfma_f32_16x16x32_bf16 v[126:129], v[150:153], v[182:185], v[126:129]
	v_mfma_f32_16x16x32_bf16 v[122:125], v[158:161], v[182:185], v[122:125]
	v_mfma_f32_16x16x32_bf16 v[110:113], v[150:153], v[190:193], v[110:113]
	v_mfma_f32_16x16x32_bf16 v[106:109], v[158:161], v[190:193], v[106:109]
	v_mfma_f32_16x16x32_bf16 v[94:97], v[150:153], v[206:209], v[94:97]
	v_mfma_f32_16x16x32_bf16 v[90:93], v[158:161], v[206:209], v[90:93]
	v_mfma_f32_16x16x32_bf16 v[78:81], v[150:153], v[214:217], v[78:81]
	v_mfma_f32_16x16x32_bf16 v[74:77], v[158:161], v[214:217], v[74:77]
	v_mfma_f32_16x16x32_bf16 v[126:129], v[154:157], v[186:189], v[126:129]
	v_mfma_f32_16x16x32_bf16 v[122:125], v[162:165], v[186:189], v[122:125]
	v_mfma_f32_16x16x32_bf16 v[110:113], v[154:157], v[202:205], v[110:113]
	v_mfma_f32_16x16x32_bf16 v[106:109], v[162:165], v[202:205], v[106:109]
	v_mfma_f32_16x16x32_bf16 v[94:97], v[154:157], v[210:213], v[94:97]
	v_mfma_f32_16x16x32_bf16 v[90:93], v[162:165], v[210:213], v[90:93]
	v_mfma_f32_16x16x32_bf16 v[78:81], v[154:157], v[218:221], v[78:81]
	v_mfma_f32_16x16x32_bf16 v[74:77], v[162:165], v[218:221], v[74:77]
	s_setprio 0
	s_setprio 1
	v_mfma_f32_16x16x32_bf16 v[118:121], v[166:169], v[182:185], v[118:121]
	v_mfma_f32_16x16x32_bf16 v[114:117], v[174:177], v[182:185], v[114:117]
	v_mfma_f32_16x16x32_bf16 v[102:105], v[166:169], v[190:193], v[102:105]
	v_mfma_f32_16x16x32_bf16 v[98:101], v[174:177], v[190:193], v[98:101]
	v_mfma_f32_16x16x32_bf16 v[86:89], v[166:169], v[206:209], v[86:89]
	v_mfma_f32_16x16x32_bf16 v[82:85], v[174:177], v[206:209], v[82:85]
	v_mfma_f32_16x16x32_bf16 v[70:73], v[166:169], v[214:217], v[70:73]
	v_mfma_f32_16x16x32_bf16 v[66:69], v[174:177], v[214:217], v[66:69]
	v_mfma_f32_16x16x32_bf16 v[118:121], v[170:173], v[186:189], v[118:121]
	v_mfma_f32_16x16x32_bf16 v[114:117], v[178:181], v[186:189], v[114:117]
	v_mfma_f32_16x16x32_bf16 v[102:105], v[170:173], v[202:205], v[102:105]
	v_mfma_f32_16x16x32_bf16 v[98:101], v[178:181], v[202:205], v[98:101]
	v_mfma_f32_16x16x32_bf16 v[86:89], v[170:173], v[210:213], v[86:89]
	v_mfma_f32_16x16x32_bf16 v[82:85], v[178:181], v[210:213], v[82:85]
	v_mfma_f32_16x16x32_bf16 v[70:73], v[170:173], v[218:221], v[70:73]
	v_mfma_f32_16x16x32_bf16 v[66:69], v[178:181], v[218:221], v[66:69]
	s_setprio 0
	s_barrier
	s_add_i32 s4, s87, s51
	v_lshl_add_u64 v[194:195], s[38:39], 0, v[134:135]
	s_mov_b32 m0, s4
	ds_read_b128 v[182:185], v149 offset:16384
	ds_read_b128 v[186:189], v149 offset:17408
	ds_read_b128 v[190:193], v149 offset:18432
	ds_read_b128 v[202:205], v149 offset:19456
	ds_read_b128 v[206:209], v149 offset:20480
	ds_read_b128 v[210:213], v149 offset:21504
	ds_read_b128 v[214:217], v149 offset:22528
	ds_read_b128 v[218:221], v149 offset:23552
	global_load_lds_dwordx4 v[194:195], off
	s_add_i32 m0, s4, 0x2000
	s_add_u32 vcc_lo, s38, 0x40000
	v_lshl_add_u64 v[198:199], s[38:39], 0, v[130:131]
	s_addc_u32 vcc_hi, s39, 0
	s_add_i32 s4, s65, s51
	global_load_lds_dwordx4 v[198:199], off
	s_mov_b32 m0, s4
	s_nop 0
	global_load_lds_dwordx4 v134, vcc
	s_add_i32 m0, s4, 0x2000
	s_nop 0
	global_load_lds_dwordx4 v130, vcc
	s_mov_b32 m0, s55
	s_nop 0
	global_load_lds_dwordx4 v136, s[40:41]
	s_mov_b32 m0, s56
	s_nop 0
	global_load_lds_dwordx4 v132, s[40:41]
	s_waitcnt vmcnt(8)
	s_waitcnt lgkmcnt(0)
	s_barrier
	s_setprio 1
	s_waitcnt lgkmcnt(0)
	v_mfma_f32_16x16x32_bf16 v[62:65], v[150:153], v[182:185], v[62:65]
	v_mfma_f32_16x16x32_bf16 v[58:61], v[158:161], v[182:185], v[58:61]
	v_mfma_f32_16x16x32_bf16 v[46:49], v[150:153], v[190:193], v[46:49]
	v_mfma_f32_16x16x32_bf16 v[42:45], v[158:161], v[190:193], v[42:45]
	v_mfma_f32_16x16x32_bf16 v[30:33], v[150:153], v[206:209], v[30:33]
	v_mfma_f32_16x16x32_bf16 v[26:29], v[158:161], v[206:209], v[26:29]
	v_mfma_f32_16x16x32_bf16 v[14:17], v[150:153], v[214:217], v[14:17]
	v_mfma_f32_16x16x32_bf16 v[10:13], v[158:161], v[214:217], v[10:13]
	v_mfma_f32_16x16x32_bf16 v[62:65], v[154:157], v[186:189], v[62:65]
	v_mfma_f32_16x16x32_bf16 v[58:61], v[162:165], v[186:189], v[58:61]
	v_mfma_f32_16x16x32_bf16 v[46:49], v[154:157], v[202:205], v[46:49]
	v_mfma_f32_16x16x32_bf16 v[42:45], v[162:165], v[202:205], v[42:45]
	v_mfma_f32_16x16x32_bf16 v[30:33], v[154:157], v[210:213], v[30:33]
	v_mfma_f32_16x16x32_bf16 v[26:29], v[162:165], v[210:213], v[26:29]
	v_mfma_f32_16x16x32_bf16 v[14:17], v[154:157], v[218:221], v[14:17]
	v_mfma_f32_16x16x32_bf16 v[10:13], v[162:165], v[218:221], v[10:13]
	s_setprio 0
	s_setprio 1
	v_mfma_f32_16x16x32_bf16 v[54:57], v[166:169], v[182:185], v[54:57]
	v_mfma_f32_16x16x32_bf16 v[50:53], v[174:177], v[182:185], v[50:53]
	v_mfma_f32_16x16x32_bf16 v[38:41], v[166:169], v[190:193], v[38:41]
	v_mfma_f32_16x16x32_bf16 v[34:37], v[174:177], v[190:193], v[34:37]
	v_mfma_f32_16x16x32_bf16 v[22:25], v[166:169], v[206:209], v[22:25]
	v_mfma_f32_16x16x32_bf16 v[18:21], v[174:177], v[206:209], v[18:21]
	v_mfma_f32_16x16x32_bf16 v[6:9], v[166:169], v[214:217], v[6:9]
	v_mfma_f32_16x16x32_bf16 v[2:5], v[174:177], v[214:217], v[2:5]
	v_mfma_f32_16x16x32_bf16 v[54:57], v[170:173], v[186:189], v[54:57]
	v_mfma_f32_16x16x32_bf16 v[50:53], v[178:181], v[186:189], v[50:53]
	v_mfma_f32_16x16x32_bf16 v[38:41], v[170:173], v[202:205], v[38:41]
	v_mfma_f32_16x16x32_bf16 v[34:37], v[178:181], v[202:205], v[34:37]
	v_mfma_f32_16x16x32_bf16 v[22:25], v[170:173], v[210:213], v[22:25]
	v_mfma_f32_16x16x32_bf16 v[18:21], v[178:181], v[210:213], v[18:21]
	v_mfma_f32_16x16x32_bf16 v[6:9], v[170:173], v[218:221], v[6:9]
	v_mfma_f32_16x16x32_bf16 v[2:5], v[178:181], v[218:221], v[2:5]
	s_setprio 0
	s_barrier
	s_add_i32 s4, 0, 0x18000
	v_add_u32_e32 v0, s4, v148
	s_add_i32 s5, 0, 0x1c000
	ds_read_b128 v[150:153], v0
	ds_read_b128 v[154:157], v0 offset:1024
	ds_read_b128 v[158:161], v0 offset:2048
	ds_read_b128 v[162:165], v0 offset:3072
	v_add_u32_e32 v0, s5, v148
	ds_read_b128 v[166:169], v0
	ds_read_b128 v[170:173], v0 offset:1024
	ds_read_b128 v[174:177], v0 offset:2048
	ds_read_b128 v[178:181], v0 offset:3072
	s_add_u32 s40, s40, 0x40000
	s_addc_u32 s41, s41, 0
	s_mov_b32 m0, s57
	ds_read_b128 v[182:185], v149 offset:32768
	ds_read_b128 v[186:189], v149 offset:33792
	ds_read_b128 v[190:193], v149 offset:34816
	ds_read_b128 v[202:205], v149 offset:35840
	ds_read_b128 v[206:209], v149 offset:36864
	ds_read_b128 v[210:213], v149 offset:37888
	ds_read_b128 v[214:217], v149 offset:38912
	ds_read_b128 v[218:221], v149 offset:39936
	global_load_lds_dwordx4 v136, s[40:41]
	s_mov_b32 m0, s58
	s_nop 0
	global_load_lds_dwordx4 v132, s[40:41]
	s_waitcnt vmcnt(8)
	s_waitcnt lgkmcnt(0)
	s_barrier
	s_setprio 1
	s_waitcnt lgkmcnt(0)
	v_mfma_f32_16x16x32_bf16 v[126:129], v[150:153], v[182:185], v[126:129]
	v_mfma_f32_16x16x32_bf16 v[122:125], v[158:161], v[182:185], v[122:125]
	v_mfma_f32_16x16x32_bf16 v[110:113], v[150:153], v[190:193], v[110:113]
	v_mfma_f32_16x16x32_bf16 v[106:109], v[158:161], v[190:193], v[106:109]
	v_mfma_f32_16x16x32_bf16 v[94:97], v[150:153], v[206:209], v[94:97]
	v_mfma_f32_16x16x32_bf16 v[90:93], v[158:161], v[206:209], v[90:93]
	v_mfma_f32_16x16x32_bf16 v[78:81], v[150:153], v[214:217], v[78:81]
	v_mfma_f32_16x16x32_bf16 v[74:77], v[158:161], v[214:217], v[74:77]
	v_mfma_f32_16x16x32_bf16 v[126:129], v[154:157], v[186:189], v[126:129]
	v_mfma_f32_16x16x32_bf16 v[122:125], v[162:165], v[186:189], v[122:125]
	v_mfma_f32_16x16x32_bf16 v[110:113], v[154:157], v[202:205], v[110:113]
	v_mfma_f32_16x16x32_bf16 v[106:109], v[162:165], v[202:205], v[106:109]
	v_mfma_f32_16x16x32_bf16 v[94:97], v[154:157], v[210:213], v[94:97]
	v_mfma_f32_16x16x32_bf16 v[90:93], v[162:165], v[210:213], v[90:93]
	v_mfma_f32_16x16x32_bf16 v[78:81], v[154:157], v[218:221], v[78:81]
	v_mfma_f32_16x16x32_bf16 v[74:77], v[162:165], v[218:221], v[74:77]
	s_setprio 0
	s_setprio 1
	v_mfma_f32_16x16x32_bf16 v[118:121], v[166:169], v[182:185], v[118:121]
	v_mfma_f32_16x16x32_bf16 v[114:117], v[174:177], v[182:185], v[114:117]
	v_mfma_f32_16x16x32_bf16 v[102:105], v[166:169], v[190:193], v[102:105]
	v_mfma_f32_16x16x32_bf16 v[98:101], v[174:177], v[190:193], v[98:101]
	v_mfma_f32_16x16x32_bf16 v[86:89], v[166:169], v[206:209], v[86:89]
	v_mfma_f32_16x16x32_bf16 v[82:85], v[174:177], v[206:209], v[82:85]
	v_mfma_f32_16x16x32_bf16 v[70:73], v[166:169], v[214:217], v[70:73]
	v_mfma_f32_16x16x32_bf16 v[66:69], v[174:177], v[214:217], v[66:69]
	v_mfma_f32_16x16x32_bf16 v[118:121], v[170:173], v[186:189], v[118:121]
	v_mfma_f32_16x16x32_bf16 v[114:117], v[178:181], v[186:189], v[114:117]
	v_mfma_f32_16x16x32_bf16 v[102:105], v[170:173], v[202:205], v[102:105]
	v_mfma_f32_16x16x32_bf16 v[98:101], v[178:181], v[202:205], v[98:101]
	v_mfma_f32_16x16x32_bf16 v[86:89], v[170:173], v[210:213], v[86:89]
	v_mfma_f32_16x16x32_bf16 v[82:85], v[178:181], v[210:213], v[82:85]
	v_mfma_f32_16x16x32_bf16 v[70:73], v[170:173], v[218:221], v[70:73]
	v_mfma_f32_16x16x32_bf16 v[66:69], v[178:181], v[218:221], v[66:69]
	s_setprio 0
	s_barrier
	s_add_i32 s4, s4, s51
	v_lshl_add_u64 v[194:195], v[194:195], 0, s[90:91]
	s_mov_b32 m0, s4
	ds_read_b128 v[182:185], v149 offset:49152
	ds_read_b128 v[186:189], v149 offset:50176
	ds_read_b128 v[190:193], v149 offset:51200
	ds_read_b128 v[202:205], v149 offset:52224
	ds_read_b128 v[206:209], v149 offset:53248
	ds_read_b128 v[210:213], v149 offset:54272
	ds_read_b128 v[214:217], v149 offset:55296
	ds_read_b128 v[218:221], v149 offset:56320
	global_load_lds_dwordx4 v[194:195], off
	s_add_i32 m0, s4, 0x2000
	s_add_u32 s38, s38, 0x40080
	v_lshl_add_u64 v[194:195], v[198:199], 0, s[90:91]
	s_addc_u32 s39, s39, 0
	s_add_i32 s4, s5, s51
	global_load_lds_dwordx4 v[194:195], off
	s_mov_b32 m0, s4
	s_nop 0
	global_load_lds_dwordx4 v134, s[38:39]
	s_add_i32 m0, s4, 0x2000
	s_nop 0
	global_load_lds_dwordx4 v130, s[38:39]
	s_mov_b32 m0, s68
	s_nop 0
	global_load_lds_dwordx4 v136, s[36:37]
	s_mov_b32 m0, s69
	s_nop 0
	global_load_lds_dwordx4 v132, s[36:37]
	s_waitcnt vmcnt(8)
	s_waitcnt lgkmcnt(0)
	s_barrier
	s_setprio 1
	s_waitcnt lgkmcnt(0)
	v_mfma_f32_16x16x32_bf16 v[62:65], v[150:153], v[182:185], v[62:65]
	v_mfma_f32_16x16x32_bf16 v[58:61], v[158:161], v[182:185], v[58:61]
	v_mfma_f32_16x16x32_bf16 v[46:49], v[150:153], v[190:193], v[46:49]
	v_mfma_f32_16x16x32_bf16 v[42:45], v[158:161], v[190:193], v[42:45]
	v_mfma_f32_16x16x32_bf16 v[30:33], v[150:153], v[206:209], v[30:33]
	v_mfma_f32_16x16x32_bf16 v[26:29], v[158:161], v[206:209], v[26:29]
	v_mfma_f32_16x16x32_bf16 v[14:17], v[150:153], v[214:217], v[14:17]
	v_mfma_f32_16x16x32_bf16 v[10:13], v[158:161], v[214:217], v[10:13]
	v_mfma_f32_16x16x32_bf16 v[62:65], v[154:157], v[186:189], v[62:65]
	v_mfma_f32_16x16x32_bf16 v[58:61], v[162:165], v[186:189], v[58:61]
	v_mfma_f32_16x16x32_bf16 v[46:49], v[154:157], v[202:205], v[46:49]
	v_mfma_f32_16x16x32_bf16 v[42:45], v[162:165], v[202:205], v[42:45]
	v_mfma_f32_16x16x32_bf16 v[30:33], v[154:157], v[210:213], v[30:33]
	v_mfma_f32_16x16x32_bf16 v[26:29], v[162:165], v[210:213], v[26:29]
	v_mfma_f32_16x16x32_bf16 v[14:17], v[154:157], v[218:221], v[14:17]
	v_mfma_f32_16x16x32_bf16 v[10:13], v[162:165], v[218:221], v[10:13]
	s_setprio 0
	s_setprio 1
	v_mfma_f32_16x16x32_bf16 v[54:57], v[166:169], v[182:185], v[54:57]
	v_mfma_f32_16x16x32_bf16 v[50:53], v[174:177], v[182:185], v[50:53]
	v_mfma_f32_16x16x32_bf16 v[38:41], v[166:169], v[190:193], v[38:41]
	v_mfma_f32_16x16x32_bf16 v[34:37], v[174:177], v[190:193], v[34:37]
	v_mfma_f32_16x16x32_bf16 v[22:25], v[166:169], v[206:209], v[22:25]
	v_mfma_f32_16x16x32_bf16 v[18:21], v[174:177], v[206:209], v[18:21]
	v_mfma_f32_16x16x32_bf16 v[6:9], v[166:169], v[214:217], v[6:9]
	v_mfma_f32_16x16x32_bf16 v[2:5], v[174:177], v[214:217], v[2:5]
	v_mfma_f32_16x16x32_bf16 v[54:57], v[170:173], v[186:189], v[54:57]
	v_mfma_f32_16x16x32_bf16 v[50:53], v[178:181], v[186:189], v[50:53]
	v_mfma_f32_16x16x32_bf16 v[38:41], v[170:173], v[202:205], v[38:41]
	v_mfma_f32_16x16x32_bf16 v[34:37], v[178:181], v[202:205], v[34:37]
	v_mfma_f32_16x16x32_bf16 v[22:25], v[170:173], v[210:213], v[22:25]
	v_mfma_f32_16x16x32_bf16 v[18:21], v[178:181], v[210:213], v[18:21]
	v_mfma_f32_16x16x32_bf16 v[6:9], v[170:173], v[218:221], v[6:9]
	v_mfma_f32_16x16x32_bf16 v[2:5], v[178:181], v[218:221], v[2:5]
	s_setprio 0
	s_barrier
	s_add_i32 s86, s86, 2
	s_add_u32 s34, s34, 0x100
	s_addc_u32 s35, s35, 0
	s_cmp_gt_u32 s86, 13
	s_cbranch_scc0 .LBB0_675
	s_and_b64 vcc, exec, s[20:21]
	s_cbranch_vccz .LBB0_678
	s_barrier

.LBB0_773:
	s_add_u32 s4, s30, s34
	s_addc_u32 s5, s31, s35
	s_add_u32 s40, s4, 0x100
	s_addc_u32 s41, s5, 0
	s_add_u32 s38, s78, s34
	s_addc_u32 s39, s85, s35
	s_add_u32 s4, s4, 0x180
	s_addc_u32 s5, s5, 0
	s_add_i32 s65, 0, 0x10000
	s_add_i32 s87, 0, 0x14000
	v_add_u32_e32 v138, s65, v231
	v_add_u32_e32 v162, s87, v231
	ds_read_b128 v[126:129], v138
	ds_read_b128 v[130:133], v138 offset:1024
	ds_read_b128 v[134:137], v138 offset:2048
	ds_read_b128 v[138:141], v138 offset:3072
	ds_read_b128 v[142:145], v162
	ds_read_b128 v[146:149], v162 offset:1024
	ds_read_b128 v[158:161], v162 offset:2048
	ds_read_b128 v[162:165], v162 offset:3072
	s_cmpk_eq_i32 s34, 0x700
	s_cselect_b32 s37, s76, s5
	s_cselect_b32 s36, s75, s4
	s_cselect_b32 s39, s23, s39
	s_cselect_b32 s38, s74, s38
	s_cselect_b32 s41, s25, s41
	s_cselect_b32 s40, s73, s40
	v_lshl_add_u64 v[194:195], v[118:119], 0, s[34:35]
	s_add_i32 m0, s56, 0xc000
	ds_read_b128 v[166:169], v242
	ds_read_b128 v[170:173], v242 offset:1024
	ds_read_b128 v[174:177], v242 offset:2048
	ds_read_b128 v[178:181], v242 offset:3072
	ds_read_b128 v[182:185], v242 offset:4096
	ds_read_b128 v[186:189], v242 offset:5120
	ds_read_b128 v[208:211], v242 offset:6144
	ds_read_b128 v[212:215], v242 offset:7168
	global_load_lds_dwordx4 v[194:195], off
	v_lshl_add_u64 v[194:195], v[120:121], 0, s[34:35]
	s_add_i32 m0, s56, 0xe000
	s_nop 0
	global_load_lds_dwordx4 v[194:195], off
	s_waitcnt vmcnt(8)
	s_waitcnt lgkmcnt(0)
	s_barrier
	s_setprio 1
	s_waitcnt lgkmcnt(0)
	v_mfma_f32_16x16x32_bf16 v[154:157], v[126:129], v[166:169], v[154:157]
	v_mfma_f32_16x16x32_bf16 v[150:153], v[134:137], v[166:169], v[150:153]
	v_mfma_f32_16x16x32_bf16 v[110:113], v[126:129], v[174:177], v[110:113]
	v_mfma_f32_16x16x32_bf16 v[106:109], v[134:137], v[174:177], v[106:109]
	v_mfma_f32_16x16x32_bf16 v[94:97], v[126:129], v[182:185], v[94:97]
	v_mfma_f32_16x16x32_bf16 v[90:93], v[134:137], v[182:185], v[90:93]
	v_mfma_f32_16x16x32_bf16 v[78:81], v[126:129], v[208:211], v[78:81]
	v_mfma_f32_16x16x32_bf16 v[74:77], v[134:137], v[208:211], v[74:77]
	v_mfma_f32_16x16x32_bf16 v[154:157], v[130:133], v[170:173], v[154:157]
	v_mfma_f32_16x16x32_bf16 v[150:153], v[138:141], v[170:173], v[150:153]
	v_mfma_f32_16x16x32_bf16 v[110:113], v[130:133], v[178:181], v[110:113]
	v_mfma_f32_16x16x32_bf16 v[106:109], v[138:141], v[178:181], v[106:109]
	v_mfma_f32_16x16x32_bf16 v[94:97], v[130:133], v[186:189], v[94:97]
	v_mfma_f32_16x16x32_bf16 v[90:93], v[138:141], v[186:189], v[90:93]
	v_mfma_f32_16x16x32_bf16 v[78:81], v[130:133], v[212:215], v[78:81]
	v_mfma_f32_16x16x32_bf16 v[74:77], v[138:141], v[212:215], v[74:77]
	s_setprio 0
	s_setprio 1
	v_mfma_f32_16x16x32_bf16 v[122:125], v[142:145], v[166:169], v[122:125]
	v_mfma_f32_16x16x32_bf16 v[114:117], v[158:161], v[166:169], v[114:117]
	v_mfma_f32_16x16x32_bf16 v[102:105], v[142:145], v[174:177], v[102:105]
	v_mfma_f32_16x16x32_bf16 v[98:101], v[158:161], v[174:177], v[98:101]
	v_mfma_f32_16x16x32_bf16 v[86:89], v[142:145], v[182:185], v[86:89]
	v_mfma_f32_16x16x32_bf16 v[82:85], v[158:161], v[182:185], v[82:85]
	v_mfma_f32_16x16x32_bf16 v[70:73], v[142:145], v[208:211], v[70:73]
	v_mfma_f32_16x16x32_bf16 v[66:69], v[158:161], v[208:211], v[66:69]
	v_mfma_f32_16x16x32_bf16 v[122:125], v[146:149], v[170:173], v[122:125]
	v_mfma_f32_16x16x32_bf16 v[114:117], v[162:165], v[170:173], v[114:117]
	v_mfma_f32_16x16x32_bf16 v[102:105], v[146:149], v[178:181], v[102:105]
	v_mfma_f32_16x16x32_bf16 v[98:101], v[162:165], v[178:181], v[98:101]
	v_mfma_f32_16x16x32_bf16 v[86:89], v[146:149], v[186:189], v[86:89]
	v_mfma_f32_16x16x32_bf16 v[82:85], v[162:165], v[186:189], v[82:85]
	v_mfma_f32_16x16x32_bf16 v[70:73], v[146:149], v[212:215], v[70:73]
	v_mfma_f32_16x16x32_bf16 v[66:69], v[162:165], v[212:215], v[66:69]
	s_setprio 0
	s_barrier
	s_add_i32 s4, s65, s51
	v_lshl_add_u64 v[194:195], s[38:39], 0, v[0:1]
	s_mov_b32 m0, s4
	ds_read_b128 v[166:169], v242 offset:16384
	ds_read_b128 v[170:173], v242 offset:17408
	ds_read_b128 v[174:177], v242 offset:18432
	ds_read_b128 v[178:181], v242 offset:19456
	ds_read_b128 v[182:185], v242 offset:20480
	ds_read_b128 v[186:189], v242 offset:21504
	ds_read_b128 v[208:211], v242 offset:22528
	ds_read_b128 v[212:215], v242 offset:23552
	global_load_lds_dwordx4 v[194:195], off
	s_add_i32 m0, s4, 0x2000
	s_add_u32 vcc_lo, s38, 0x40000
	v_lshl_add_u64 v[198:199], s[38:39], 0, v[190:191]
	s_addc_u32 vcc_hi, s39, 0
	s_add_i32 s4, s87, s51
	global_load_lds_dwordx4 v[198:199], off
	s_mov_b32 m0, s4
	s_nop 0
	global_load_lds_dwordx4 v0, vcc
	s_add_i32 m0, s4, 0x2000
	s_nop 0
	global_load_lds_dwordx4 v190, vcc
	s_mov_b32 m0, s56
	s_nop 0
	global_load_lds_dwordx4 v202, s[40:41]
	s_mov_b32 m0, s57
	s_nop 0
	global_load_lds_dwordx4 v192, s[40:41]
	s_waitcnt vmcnt(8)
	s_waitcnt lgkmcnt(0)
	s_barrier
	s_setprio 1
	s_waitcnt lgkmcnt(0)
	v_mfma_f32_16x16x32_bf16 v[62:65], v[126:129], v[166:169], v[62:65]
	v_mfma_f32_16x16x32_bf16 v[58:61], v[134:137], v[166:169], v[58:61]
	v_mfma_f32_16x16x32_bf16 v[46:49], v[126:129], v[174:177], v[46:49]
	v_mfma_f32_16x16x32_bf16 v[42:45], v[134:137], v[174:177], v[42:45]
	v_mfma_f32_16x16x32_bf16 v[30:33], v[126:129], v[182:185], v[30:33]
	v_mfma_f32_16x16x32_bf16 v[26:29], v[134:137], v[182:185], v[26:29]
	v_mfma_f32_16x16x32_bf16 v[14:17], v[126:129], v[208:211], v[14:17]
	v_mfma_f32_16x16x32_bf16 v[10:13], v[134:137], v[208:211], v[10:13]
	v_mfma_f32_16x16x32_bf16 v[62:65], v[130:133], v[170:173], v[62:65]
	v_mfma_f32_16x16x32_bf16 v[58:61], v[138:141], v[170:173], v[58:61]
	v_mfma_f32_16x16x32_bf16 v[46:49], v[130:133], v[178:181], v[46:49]
	v_mfma_f32_16x16x32_bf16 v[42:45], v[138:141], v[178:181], v[42:45]
	v_mfma_f32_16x16x32_bf16 v[30:33], v[130:133], v[186:189], v[30:33]
	v_mfma_f32_16x16x32_bf16 v[26:29], v[138:141], v[186:189], v[26:29]
	v_mfma_f32_16x16x32_bf16 v[14:17], v[130:133], v[212:215], v[14:17]
	v_mfma_f32_16x16x32_bf16 v[10:13], v[138:141], v[212:215], v[10:13]
	s_setprio 0
	s_setprio 1
	v_mfma_f32_16x16x32_bf16 v[54:57], v[142:145], v[166:169], v[54:57]
	v_mfma_f32_16x16x32_bf16 v[50:53], v[158:161], v[166:169], v[50:53]
	v_mfma_f32_16x16x32_bf16 v[38:41], v[142:145], v[174:177], v[38:41]
	v_mfma_f32_16x16x32_bf16 v[34:37], v[158:161], v[174:177], v[34:37]
	v_mfma_f32_16x16x32_bf16 v[22:25], v[142:145], v[182:185], v[22:25]
	v_mfma_f32_16x16x32_bf16 v[18:21], v[158:161], v[182:185], v[18:21]
	v_mfma_f32_16x16x32_bf16 v[6:9], v[142:145], v[208:211], v[6:9]
	v_mfma_f32_16x16x32_bf16 v[2:5], v[158:161], v[208:211], v[2:5]
	v_mfma_f32_16x16x32_bf16 v[54:57], v[146:149], v[170:173], v[54:57]
	v_mfma_f32_16x16x32_bf16 v[50:53], v[162:165], v[170:173], v[50:53]
	v_mfma_f32_16x16x32_bf16 v[38:41], v[146:149], v[178:181], v[38:41]
	v_mfma_f32_16x16x32_bf16 v[34:37], v[162:165], v[178:181], v[34:37]
	v_mfma_f32_16x16x32_bf16 v[22:25], v[146:149], v[186:189], v[22:25]
	v_mfma_f32_16x16x32_bf16 v[18:21], v[162:165], v[186:189], v[18:21]
	v_mfma_f32_16x16x32_bf16 v[6:9], v[146:149], v[212:215], v[6:9]
	v_mfma_f32_16x16x32_bf16 v[2:5], v[162:165], v[212:215], v[2:5]
	s_setprio 0
	s_barrier
	s_add_i32 s4, 0, 0x18000
	s_add_i32 s5, 0, 0x1c000
	v_add_u32_e32 v138, s4, v231
	v_add_u32_e32 v162, s5, v231
	ds_read_b128 v[126:129], v138
	ds_read_b128 v[130:133], v138 offset:1024
	ds_read_b128 v[134:137], v138 offset:2048
	ds_read_b128 v[138:141], v138 offset:3072
	ds_read_b128 v[142:145], v162
	ds_read_b128 v[146:149], v162 offset:1024
	ds_read_b128 v[158:161], v162 offset:2048
	ds_read_b128 v[162:165], v162 offset:3072
	s_add_u32 s40, s40, 0x40000
	s_addc_u32 s41, s41, 0
	s_mov_b32 m0, s58
	ds_read_b128 v[166:169], v242 offset:32768
	ds_read_b128 v[170:173], v242 offset:33792
	ds_read_b128 v[174:177], v242 offset:34816
	ds_read_b128 v[178:181], v242 offset:35840
	ds_read_b128 v[182:185], v242 offset:36864
	ds_read_b128 v[186:189], v242 offset:37888
	ds_read_b128 v[208:211], v242 offset:38912
	ds_read_b128 v[212:215], v242 offset:39936
	global_load_lds_dwordx4 v202, s[40:41]
	s_mov_b32 m0, s59
	s_nop 0
	global_load_lds_dwordx4 v192, s[40:41]
	s_waitcnt vmcnt(8)
	s_waitcnt lgkmcnt(0)
	s_barrier
	s_setprio 1
	s_waitcnt lgkmcnt(0)
	v_mfma_f32_16x16x32_bf16 v[154:157], v[126:129], v[166:169], v[154:157]
	v_mfma_f32_16x16x32_bf16 v[150:153], v[134:137], v[166:169], v[150:153]
	v_mfma_f32_16x16x32_bf16 v[110:113], v[126:129], v[174:177], v[110:113]
	v_mfma_f32_16x16x32_bf16 v[106:109], v[134:137], v[174:177], v[106:109]
	v_mfma_f32_16x16x32_bf16 v[94:97], v[126:129], v[182:185], v[94:97]
	v_mfma_f32_16x16x32_bf16 v[90:93], v[134:137], v[182:185], v[90:93]
	v_mfma_f32_16x16x32_bf16 v[78:81], v[126:129], v[208:211], v[78:81]
	v_mfma_f32_16x16x32_bf16 v[74:77], v[134:137], v[208:211], v[74:77]
	v_mfma_f32_16x16x32_bf16 v[154:157], v[130:133], v[170:173], v[154:157]
	v_mfma_f32_16x16x32_bf16 v[150:153], v[138:141], v[170:173], v[150:153]
	v_mfma_f32_16x16x32_bf16 v[110:113], v[130:133], v[178:181], v[110:113]
	v_mfma_f32_16x16x32_bf16 v[106:109], v[138:141], v[178:181], v[106:109]
	v_mfma_f32_16x16x32_bf16 v[94:97], v[130:133], v[186:189], v[94:97]
	v_mfma_f32_16x16x32_bf16 v[90:93], v[138:141], v[186:189], v[90:93]
	v_mfma_f32_16x16x32_bf16 v[78:81], v[130:133], v[212:215], v[78:81]
	v_mfma_f32_16x16x32_bf16 v[74:77], v[138:141], v[212:215], v[74:77]
	s_setprio 0
	s_setprio 1
	v_mfma_f32_16x16x32_bf16 v[122:125], v[142:145], v[166:169], v[122:125]
	v_mfma_f32_16x16x32_bf16 v[114:117], v[158:161], v[166:169], v[114:117]
	v_mfma_f32_16x16x32_bf16 v[102:105], v[142:145], v[174:177], v[102:105]
	v_mfma_f32_16x16x32_bf16 v[98:101], v[158:161], v[174:177], v[98:101]
	v_mfma_f32_16x16x32_bf16 v[86:89], v[142:145], v[182:185], v[86:89]
	v_mfma_f32_16x16x32_bf16 v[82:85], v[158:161], v[182:185], v[82:85]
	v_mfma_f32_16x16x32_bf16 v[70:73], v[142:145], v[208:211], v[70:73]
	v_mfma_f32_16x16x32_bf16 v[66:69], v[158:161], v[208:211], v[66:69]
	v_mfma_f32_16x16x32_bf16 v[122:125], v[146:149], v[170:173], v[122:125]
	v_mfma_f32_16x16x32_bf16 v[114:117], v[162:165], v[170:173], v[114:117]
	v_mfma_f32_16x16x32_bf16 v[102:105], v[146:149], v[178:181], v[102:105]
	v_mfma_f32_16x16x32_bf16 v[98:101], v[162:165], v[178:181], v[98:101]
	v_mfma_f32_16x16x32_bf16 v[86:89], v[146:149], v[186:189], v[86:89]
	v_mfma_f32_16x16x32_bf16 v[82:85], v[162:165], v[186:189], v[82:85]
	v_mfma_f32_16x16x32_bf16 v[70:73], v[146:149], v[212:215], v[70:73]
	v_mfma_f32_16x16x32_bf16 v[66:69], v[162:165], v[212:215], v[66:69]
	s_setprio 0
	s_barrier
	s_add_i32 s4, s4, s51
	v_lshl_add_u64 v[194:195], v[194:195], 0, s[90:91]
	s_mov_b32 m0, s4
	ds_read_b128 v[166:169], v242 offset:49152
	ds_read_b128 v[170:173], v242 offset:50176
	ds_read_b128 v[174:177], v242 offset:51200
	ds_read_b128 v[178:181], v242 offset:52224
	ds_read_b128 v[182:185], v242 offset:53248
	ds_read_b128 v[186:189], v242 offset:54272
	ds_read_b128 v[208:211], v242 offset:55296
	ds_read_b128 v[212:215], v242 offset:56320
	global_load_lds_dwordx4 v[194:195], off
	s_add_i32 m0, s4, 0x2000
	s_add_u32 s38, s38, 0x40080
	v_lshl_add_u64 v[194:195], v[198:199], 0, s[90:91]
	s_addc_u32 s39, s39, 0
	s_add_i32 s4, s5, s51
	global_load_lds_dwordx4 v[194:195], off
	s_mov_b32 m0, s4
	s_nop 0
	global_load_lds_dwordx4 v0, s[38:39]
	s_add_i32 m0, s4, 0x2000
	s_nop 0
	global_load_lds_dwordx4 v190, s[38:39]
	s_mov_b32 m0, s68
	s_nop 0
	global_load_lds_dwordx4 v202, s[36:37]
	s_mov_b32 m0, s69
	s_nop 0
	global_load_lds_dwordx4 v192, s[36:37]
	s_waitcnt vmcnt(8)
	s_waitcnt lgkmcnt(0)
	s_barrier
	s_setprio 1
	s_waitcnt lgkmcnt(0)
	v_mfma_f32_16x16x32_bf16 v[62:65], v[126:129], v[166:169], v[62:65]
	v_mfma_f32_16x16x32_bf16 v[58:61], v[134:137], v[166:169], v[58:61]
	v_mfma_f32_16x16x32_bf16 v[46:49], v[126:129], v[174:177], v[46:49]
	v_mfma_f32_16x16x32_bf16 v[42:45], v[134:137], v[174:177], v[42:45]
	v_mfma_f32_16x16x32_bf16 v[30:33], v[126:129], v[182:185], v[30:33]
	v_mfma_f32_16x16x32_bf16 v[26:29], v[134:137], v[182:185], v[26:29]
	v_mfma_f32_16x16x32_bf16 v[14:17], v[126:129], v[208:211], v[14:17]
	v_mfma_f32_16x16x32_bf16 v[10:13], v[134:137], v[208:211], v[10:13]
	v_mfma_f32_16x16x32_bf16 v[62:65], v[130:133], v[170:173], v[62:65]
	v_mfma_f32_16x16x32_bf16 v[58:61], v[138:141], v[170:173], v[58:61]
	v_mfma_f32_16x16x32_bf16 v[46:49], v[130:133], v[178:181], v[46:49]
	v_mfma_f32_16x16x32_bf16 v[42:45], v[138:141], v[178:181], v[42:45]
	v_mfma_f32_16x16x32_bf16 v[30:33], v[130:133], v[186:189], v[30:33]
	v_mfma_f32_16x16x32_bf16 v[26:29], v[138:141], v[186:189], v[26:29]
	v_mfma_f32_16x16x32_bf16 v[14:17], v[130:133], v[212:215], v[14:17]
	v_mfma_f32_16x16x32_bf16 v[10:13], v[138:141], v[212:215], v[10:13]
	s_setprio 0
	s_setprio 1
	v_mfma_f32_16x16x32_bf16 v[54:57], v[142:145], v[166:169], v[54:57]
	v_mfma_f32_16x16x32_bf16 v[50:53], v[158:161], v[166:169], v[50:53]
	v_mfma_f32_16x16x32_bf16 v[38:41], v[142:145], v[174:177], v[38:41]
	v_mfma_f32_16x16x32_bf16 v[34:37], v[158:161], v[174:177], v[34:37]
	v_mfma_f32_16x16x32_bf16 v[22:25], v[142:145], v[182:185], v[22:25]
	v_mfma_f32_16x16x32_bf16 v[18:21], v[158:161], v[182:185], v[18:21]
	v_mfma_f32_16x16x32_bf16 v[6:9], v[142:145], v[208:211], v[6:9]
	v_mfma_f32_16x16x32_bf16 v[2:5], v[158:161], v[208:211], v[2:5]
	v_mfma_f32_16x16x32_bf16 v[54:57], v[146:149], v[170:173], v[54:57]
	v_mfma_f32_16x16x32_bf16 v[50:53], v[162:165], v[170:173], v[50:53]
	v_mfma_f32_16x16x32_bf16 v[38:41], v[146:149], v[178:181], v[38:41]
	v_mfma_f32_16x16x32_bf16 v[34:37], v[162:165], v[178:181], v[34:37]
	v_mfma_f32_16x16x32_bf16 v[22:25], v[146:149], v[186:189], v[22:25]
	v_mfma_f32_16x16x32_bf16 v[18:21], v[162:165], v[186:189], v[18:21]
	v_mfma_f32_16x16x32_bf16 v[6:9], v[146:149], v[212:215], v[6:9]
	v_mfma_f32_16x16x32_bf16 v[2:5], v[162:165], v[212:215], v[2:5]
	s_setprio 0
	s_barrier
	s_add_i32 s86, s86, 2
	s_add_u32 s34, s34, 0x100
	s_addc_u32 s35, s35, 0
	s_cmp_gt_u32 s86, 13
	s_cbranch_scc0 .LBB0_773
	s_and_b64 vcc, exec, s[18:19]
	s_cbranch_vccz .LBB0_776
	s_barrier

.LBB0_861:
	s_add_u32 s4, s30, s34
	s_addc_u32 s5, s31, s35
	s_add_u32 s40, s4, 0x100
	s_addc_u32 s41, s5, 0
	s_add_u32 s38, s78, s34
	s_addc_u32 s39, s85, s35
	s_add_u32 s4, s4, 0x180
	s_addc_u32 s5, s5, 0
	s_add_i32 s65, 0, 0x10000
	s_add_i32 s87, 0, 0x14000
	v_add_u32_e32 v162, s65, v152
	v_add_u32_e32 v178, s87, v152
	ds_read_b128 v[146:149], v162
	ds_read_b128 v[154:157], v162 offset:1024
	ds_read_b128 v[158:161], v162 offset:2048
	ds_read_b128 v[162:165], v162 offset:3072
	ds_read_b128 v[166:169], v178
	ds_read_b128 v[170:173], v178 offset:1024
	ds_read_b128 v[174:177], v178 offset:2048
	ds_read_b128 v[178:181], v178 offset:3072
	s_cmpk_eq_i32 s34, 0x700
	s_cselect_b32 s37, s76, s5
	s_cselect_b32 s36, s75, s4
	s_cselect_b32 s39, s23, s39
	s_cselect_b32 s38, s74, s38
	s_cselect_b32 s41, s25, s41
	s_cselect_b32 s40, s73, s40
	v_lshl_add_u64 v[194:195], v[142:143], 0, s[34:35]
	s_add_i32 m0, s56, 0xc000
	ds_read_b128 v[182:185], v153
	ds_read_b128 v[186:189], v153 offset:1024
	ds_read_b128 v[190:193], v153 offset:2048
	ds_read_b128 v[202:205], v153 offset:3072
	ds_read_b128 v[206:209], v153 offset:4096
	ds_read_b128 v[210:213], v153 offset:5120
	ds_read_b128 v[214:217], v153 offset:6144
	ds_read_b128 v[218:221], v153 offset:7168
	global_load_lds_dwordx4 v[194:195], off
	v_lshl_add_u64 v[194:195], v[144:145], 0, s[34:35]
	s_add_i32 m0, s56, 0xe000
	s_nop 0
	global_load_lds_dwordx4 v[194:195], off
	s_waitcnt vmcnt(8)
	s_waitcnt lgkmcnt(0)
	s_barrier
	s_setprio 1
	s_waitcnt lgkmcnt(0)
	v_mfma_f32_16x16x32_bf16 v[126:129], v[146:149], v[182:185], v[126:129]
	v_mfma_f32_16x16x32_bf16 v[122:125], v[158:161], v[182:185], v[122:125]
	v_mfma_f32_16x16x32_bf16 v[110:113], v[146:149], v[190:193], v[110:113]
	v_mfma_f32_16x16x32_bf16 v[106:109], v[158:161], v[190:193], v[106:109]
	v_mfma_f32_16x16x32_bf16 v[94:97], v[146:149], v[206:209], v[94:97]
	v_mfma_f32_16x16x32_bf16 v[90:93], v[158:161], v[206:209], v[90:93]
	v_mfma_f32_16x16x32_bf16 v[78:81], v[146:149], v[214:217], v[78:81]
	v_mfma_f32_16x16x32_bf16 v[74:77], v[158:161], v[214:217], v[74:77]
	v_mfma_f32_16x16x32_bf16 v[126:129], v[154:157], v[186:189], v[126:129]
	v_mfma_f32_16x16x32_bf16 v[122:125], v[162:165], v[186:189], v[122:125]
	v_mfma_f32_16x16x32_bf16 v[110:113], v[154:157], v[202:205], v[110:113]
	v_mfma_f32_16x16x32_bf16 v[106:109], v[162:165], v[202:205], v[106:109]
	v_mfma_f32_16x16x32_bf16 v[94:97], v[154:157], v[210:213], v[94:97]
	v_mfma_f32_16x16x32_bf16 v[90:93], v[162:165], v[210:213], v[90:93]
	v_mfma_f32_16x16x32_bf16 v[78:81], v[154:157], v[218:221], v[78:81]
	v_mfma_f32_16x16x32_bf16 v[74:77], v[162:165], v[218:221], v[74:77]
	s_setprio 0
	s_setprio 1
	v_mfma_f32_16x16x32_bf16 v[118:121], v[166:169], v[182:185], v[118:121]
	v_mfma_f32_16x16x32_bf16 v[114:117], v[174:177], v[182:185], v[114:117]
	v_mfma_f32_16x16x32_bf16 v[102:105], v[166:169], v[190:193], v[102:105]
	v_mfma_f32_16x16x32_bf16 v[98:101], v[174:177], v[190:193], v[98:101]
	v_mfma_f32_16x16x32_bf16 v[86:89], v[166:169], v[206:209], v[86:89]
	v_mfma_f32_16x16x32_bf16 v[82:85], v[174:177], v[206:209], v[82:85]
	v_mfma_f32_16x16x32_bf16 v[70:73], v[166:169], v[214:217], v[70:73]
	v_mfma_f32_16x16x32_bf16 v[66:69], v[174:177], v[214:217], v[66:69]
	v_mfma_f32_16x16x32_bf16 v[118:121], v[170:173], v[186:189], v[118:121]
	v_mfma_f32_16x16x32_bf16 v[114:117], v[178:181], v[186:189], v[114:117]
	v_mfma_f32_16x16x32_bf16 v[102:105], v[170:173], v[202:205], v[102:105]
	v_mfma_f32_16x16x32_bf16 v[98:101], v[178:181], v[202:205], v[98:101]
	v_mfma_f32_16x16x32_bf16 v[86:89], v[170:173], v[210:213], v[86:89]
	v_mfma_f32_16x16x32_bf16 v[82:85], v[178:181], v[210:213], v[82:85]
	v_mfma_f32_16x16x32_bf16 v[70:73], v[170:173], v[218:221], v[70:73]
	v_mfma_f32_16x16x32_bf16 v[66:69], v[178:181], v[218:221], v[66:69]
	s_setprio 0
	s_barrier
	s_add_i32 s4, s65, s51
	v_lshl_add_u64 v[194:195], s[38:39], 0, v[134:135]
	s_mov_b32 m0, s4
	ds_read_b128 v[182:185], v153 offset:16384
	ds_read_b128 v[186:189], v153 offset:17408
	ds_read_b128 v[190:193], v153 offset:18432
	ds_read_b128 v[202:205], v153 offset:19456
	ds_read_b128 v[206:209], v153 offset:20480
	ds_read_b128 v[210:213], v153 offset:21504
	ds_read_b128 v[214:217], v153 offset:22528
	ds_read_b128 v[218:221], v153 offset:23552
	global_load_lds_dwordx4 v[194:195], off
	s_add_i32 m0, s4, 0x2000
	s_add_u32 vcc_lo, s38, 0x40000
	v_lshl_add_u64 v[198:199], s[38:39], 0, v[130:131]
	s_addc_u32 vcc_hi, s39, 0
	s_add_i32 s4, s87, s51
	global_load_lds_dwordx4 v[198:199], off
	s_mov_b32 m0, s4
	s_nop 0
	global_load_lds_dwordx4 v134, vcc
	s_add_i32 m0, s4, 0x2000
	s_nop 0
	global_load_lds_dwordx4 v130, vcc
	s_mov_b32 m0, s56
	s_nop 0
	global_load_lds_dwordx4 v136, s[40:41]
	s_mov_b32 m0, s57
	s_nop 0
	global_load_lds_dwordx4 v132, s[40:41]
	s_waitcnt vmcnt(8)
	s_waitcnt lgkmcnt(0)
	s_barrier
	s_setprio 1
	s_waitcnt lgkmcnt(0)
	v_mfma_f32_16x16x32_bf16 v[62:65], v[146:149], v[182:185], v[62:65]
	v_mfma_f32_16x16x32_bf16 v[58:61], v[158:161], v[182:185], v[58:61]
	v_mfma_f32_16x16x32_bf16 v[46:49], v[146:149], v[190:193], v[46:49]
	v_mfma_f32_16x16x32_bf16 v[42:45], v[158:161], v[190:193], v[42:45]
	v_mfma_f32_16x16x32_bf16 v[30:33], v[146:149], v[206:209], v[30:33]
	v_mfma_f32_16x16x32_bf16 v[26:29], v[158:161], v[206:209], v[26:29]
	v_mfma_f32_16x16x32_bf16 v[14:17], v[146:149], v[214:217], v[14:17]
	v_mfma_f32_16x16x32_bf16 v[10:13], v[158:161], v[214:217], v[10:13]
	v_mfma_f32_16x16x32_bf16 v[62:65], v[154:157], v[186:189], v[62:65]
	v_mfma_f32_16x16x32_bf16 v[58:61], v[162:165], v[186:189], v[58:61]
	v_mfma_f32_16x16x32_bf16 v[46:49], v[154:157], v[202:205], v[46:49]
	v_mfma_f32_16x16x32_bf16 v[42:45], v[162:165], v[202:205], v[42:45]
	v_mfma_f32_16x16x32_bf16 v[30:33], v[154:157], v[210:213], v[30:33]
	v_mfma_f32_16x16x32_bf16 v[26:29], v[162:165], v[210:213], v[26:29]
	v_mfma_f32_16x16x32_bf16 v[14:17], v[154:157], v[218:221], v[14:17]
	v_mfma_f32_16x16x32_bf16 v[10:13], v[162:165], v[218:221], v[10:13]
	s_setprio 0
	s_setprio 1
	v_mfma_f32_16x16x32_bf16 v[54:57], v[166:169], v[182:185], v[54:57]
	v_mfma_f32_16x16x32_bf16 v[50:53], v[174:177], v[182:185], v[50:53]
	v_mfma_f32_16x16x32_bf16 v[38:41], v[166:169], v[190:193], v[38:41]
	v_mfma_f32_16x16x32_bf16 v[34:37], v[174:177], v[190:193], v[34:37]
	v_mfma_f32_16x16x32_bf16 v[22:25], v[166:169], v[206:209], v[22:25]
	v_mfma_f32_16x16x32_bf16 v[18:21], v[174:177], v[206:209], v[18:21]
	v_mfma_f32_16x16x32_bf16 v[6:9], v[166:169], v[214:217], v[6:9]
	v_mfma_f32_16x16x32_bf16 v[2:5], v[174:177], v[214:217], v[2:5]
	v_mfma_f32_16x16x32_bf16 v[54:57], v[170:173], v[186:189], v[54:57]
	v_mfma_f32_16x16x32_bf16 v[50:53], v[178:181], v[186:189], v[50:53]
	v_mfma_f32_16x16x32_bf16 v[38:41], v[170:173], v[202:205], v[38:41]
	v_mfma_f32_16x16x32_bf16 v[34:37], v[178:181], v[202:205], v[34:37]
	v_mfma_f32_16x16x32_bf16 v[22:25], v[170:173], v[210:213], v[22:25]
	v_mfma_f32_16x16x32_bf16 v[18:21], v[178:181], v[210:213], v[18:21]
	v_mfma_f32_16x16x32_bf16 v[6:9], v[170:173], v[218:221], v[6:9]
	v_mfma_f32_16x16x32_bf16 v[2:5], v[178:181], v[218:221], v[2:5]
	s_setprio 0
	s_barrier
	s_add_i32 s4, 0, 0x18000
	s_add_i32 s5, 0, 0x1c000
	v_add_u32_e32 v162, s4, v152
	v_add_u32_e32 v178, s5, v152
	ds_read_b128 v[146:149], v162
	ds_read_b128 v[154:157], v162 offset:1024
	ds_read_b128 v[158:161], v162 offset:2048
	ds_read_b128 v[162:165], v162 offset:3072
	ds_read_b128 v[166:169], v178
	ds_read_b128 v[170:173], v178 offset:1024
	ds_read_b128 v[174:177], v178 offset:2048
	ds_read_b128 v[178:181], v178 offset:3072
	s_add_u32 s40, s40, 0x40000
	s_addc_u32 s41, s41, 0
	s_mov_b32 m0, s58
	ds_read_b128 v[182:185], v153 offset:32768
	ds_read_b128 v[186:189], v153 offset:33792
	ds_read_b128 v[190:193], v153 offset:34816
	ds_read_b128 v[202:205], v153 offset:35840
	ds_read_b128 v[206:209], v153 offset:36864
	ds_read_b128 v[210:213], v153 offset:37888
	ds_read_b128 v[214:217], v153 offset:38912
	ds_read_b128 v[218:221], v153 offset:39936
	global_load_lds_dwordx4 v136, s[40:41]
	s_mov_b32 m0, s59
	s_nop 0
	global_load_lds_dwordx4 v132, s[40:41]
	s_waitcnt vmcnt(8)
	s_waitcnt lgkmcnt(0)
	s_barrier
	s_setprio 1
	s_waitcnt lgkmcnt(0)
	v_mfma_f32_16x16x32_bf16 v[126:129], v[146:149], v[182:185], v[126:129]
	v_mfma_f32_16x16x32_bf16 v[122:125], v[158:161], v[182:185], v[122:125]
	v_mfma_f32_16x16x32_bf16 v[110:113], v[146:149], v[190:193], v[110:113]
	v_mfma_f32_16x16x32_bf16 v[106:109], v[158:161], v[190:193], v[106:109]
	v_mfma_f32_16x16x32_bf16 v[94:97], v[146:149], v[206:209], v[94:97]
	v_mfma_f32_16x16x32_bf16 v[90:93], v[158:161], v[206:209], v[90:93]
	v_mfma_f32_16x16x32_bf16 v[78:81], v[146:149], v[214:217], v[78:81]
	v_mfma_f32_16x16x32_bf16 v[74:77], v[158:161], v[214:217], v[74:77]
	v_mfma_f32_16x16x32_bf16 v[126:129], v[154:157], v[186:189], v[126:129]
	v_mfma_f32_16x16x32_bf16 v[122:125], v[162:165], v[186:189], v[122:125]
	v_mfma_f32_16x16x32_bf16 v[110:113], v[154:157], v[202:205], v[110:113]
	v_mfma_f32_16x16x32_bf16 v[106:109], v[162:165], v[202:205], v[106:109]
	v_mfma_f32_16x16x32_bf16 v[94:97], v[154:157], v[210:213], v[94:97]
	v_mfma_f32_16x16x32_bf16 v[90:93], v[162:165], v[210:213], v[90:93]
	v_mfma_f32_16x16x32_bf16 v[78:81], v[154:157], v[218:221], v[78:81]
	v_mfma_f32_16x16x32_bf16 v[74:77], v[162:165], v[218:221], v[74:77]
	s_setprio 0
	s_setprio 1
	v_mfma_f32_16x16x32_bf16 v[118:121], v[166:169], v[182:185], v[118:121]
	v_mfma_f32_16x16x32_bf16 v[114:117], v[174:177], v[182:185], v[114:117]
	v_mfma_f32_16x16x32_bf16 v[102:105], v[166:169], v[190:193], v[102:105]
	v_mfma_f32_16x16x32_bf16 v[98:101], v[174:177], v[190:193], v[98:101]
	v_mfma_f32_16x16x32_bf16 v[86:89], v[166:169], v[206:209], v[86:89]
	v_mfma_f32_16x16x32_bf16 v[82:85], v[174:177], v[206:209], v[82:85]
	v_mfma_f32_16x16x32_bf16 v[70:73], v[166:169], v[214:217], v[70:73]
	v_mfma_f32_16x16x32_bf16 v[66:69], v[174:177], v[214:217], v[66:69]
	v_mfma_f32_16x16x32_bf16 v[118:121], v[170:173], v[186:189], v[118:121]
	v_mfma_f32_16x16x32_bf16 v[114:117], v[178:181], v[186:189], v[114:117]
	v_mfma_f32_16x16x32_bf16 v[102:105], v[170:173], v[202:205], v[102:105]
	v_mfma_f32_16x16x32_bf16 v[98:101], v[178:181], v[202:205], v[98:101]
	v_mfma_f32_16x16x32_bf16 v[86:89], v[170:173], v[210:213], v[86:89]
	v_mfma_f32_16x16x32_bf16 v[82:85], v[178:181], v[210:213], v[82:85]
	v_mfma_f32_16x16x32_bf16 v[70:73], v[170:173], v[218:221], v[70:73]
	v_mfma_f32_16x16x32_bf16 v[66:69], v[178:181], v[218:221], v[66:69]
	s_setprio 0
	s_barrier
	s_add_i32 s4, s4, s51
	v_lshl_add_u64 v[194:195], v[194:195], 0, s[90:91]
	s_mov_b32 m0, s4
	ds_read_b128 v[182:185], v153 offset:49152
	ds_read_b128 v[186:189], v153 offset:50176
	ds_read_b128 v[190:193], v153 offset:51200
	ds_read_b128 v[202:205], v153 offset:52224
	ds_read_b128 v[206:209], v153 offset:53248
	ds_read_b128 v[210:213], v153 offset:54272
	ds_read_b128 v[214:217], v153 offset:55296
	ds_read_b128 v[218:221], v153 offset:56320
	global_load_lds_dwordx4 v[194:195], off
	s_add_i32 m0, s4, 0x2000
	s_add_u32 s38, s38, 0x40080
	v_lshl_add_u64 v[194:195], v[198:199], 0, s[90:91]
	s_addc_u32 s39, s39, 0
	s_add_i32 s4, s5, s51
	global_load_lds_dwordx4 v[194:195], off
	s_mov_b32 m0, s4
	s_nop 0
	global_load_lds_dwordx4 v134, s[38:39]
	s_add_i32 m0, s4, 0x2000
	s_nop 0
	global_load_lds_dwordx4 v130, s[38:39]
	s_mov_b32 m0, s68
	s_nop 0
	global_load_lds_dwordx4 v136, s[36:37]
	s_mov_b32 m0, s69
	s_nop 0
	global_load_lds_dwordx4 v132, s[36:37]
	s_waitcnt vmcnt(8)
	s_waitcnt lgkmcnt(0)
	s_barrier
	s_setprio 1
	s_waitcnt lgkmcnt(0)
	v_mfma_f32_16x16x32_bf16 v[62:65], v[146:149], v[182:185], v[62:65]
	v_mfma_f32_16x16x32_bf16 v[58:61], v[158:161], v[182:185], v[58:61]
	v_mfma_f32_16x16x32_bf16 v[46:49], v[146:149], v[190:193], v[46:49]
	v_mfma_f32_16x16x32_bf16 v[42:45], v[158:161], v[190:193], v[42:45]
	v_mfma_f32_16x16x32_bf16 v[30:33], v[146:149], v[206:209], v[30:33]
	v_mfma_f32_16x16x32_bf16 v[26:29], v[158:161], v[206:209], v[26:29]
	v_mfma_f32_16x16x32_bf16 v[14:17], v[146:149], v[214:217], v[14:17]
	v_mfma_f32_16x16x32_bf16 v[10:13], v[158:161], v[214:217], v[10:13]
	v_mfma_f32_16x16x32_bf16 v[62:65], v[154:157], v[186:189], v[62:65]
	v_mfma_f32_16x16x32_bf16 v[58:61], v[162:165], v[186:189], v[58:61]
	v_mfma_f32_16x16x32_bf16 v[46:49], v[154:157], v[202:205], v[46:49]
	v_mfma_f32_16x16x32_bf16 v[42:45], v[162:165], v[202:205], v[42:45]
	v_mfma_f32_16x16x32_bf16 v[30:33], v[154:157], v[210:213], v[30:33]
	v_mfma_f32_16x16x32_bf16 v[26:29], v[162:165], v[210:213], v[26:29]
	v_mfma_f32_16x16x32_bf16 v[14:17], v[154:157], v[218:221], v[14:17]
	v_mfma_f32_16x16x32_bf16 v[10:13], v[162:165], v[218:221], v[10:13]
	s_setprio 0
	s_setprio 1
	v_mfma_f32_16x16x32_bf16 v[54:57], v[166:169], v[182:185], v[54:57]
	v_mfma_f32_16x16x32_bf16 v[50:53], v[174:177], v[182:185], v[50:53]
	v_mfma_f32_16x16x32_bf16 v[38:41], v[166:169], v[190:193], v[38:41]
	v_mfma_f32_16x16x32_bf16 v[34:37], v[174:177], v[190:193], v[34:37]
	v_mfma_f32_16x16x32_bf16 v[22:25], v[166:169], v[206:209], v[22:25]
	v_mfma_f32_16x16x32_bf16 v[18:21], v[174:177], v[206:209], v[18:21]
	v_mfma_f32_16x16x32_bf16 v[6:9], v[166:169], v[214:217], v[6:9]
	v_mfma_f32_16x16x32_bf16 v[2:5], v[174:177], v[214:217], v[2:5]
	v_mfma_f32_16x16x32_bf16 v[54:57], v[170:173], v[186:189], v[54:57]
	v_mfma_f32_16x16x32_bf16 v[50:53], v[178:181], v[186:189], v[50:53]
	v_mfma_f32_16x16x32_bf16 v[38:41], v[170:173], v[202:205], v[38:41]
	v_mfma_f32_16x16x32_bf16 v[34:37], v[178:181], v[202:205], v[34:37]
	v_mfma_f32_16x16x32_bf16 v[22:25], v[170:173], v[210:213], v[22:25]
	v_mfma_f32_16x16x32_bf16 v[18:21], v[178:181], v[210:213], v[18:21]
	v_mfma_f32_16x16x32_bf16 v[6:9], v[170:173], v[218:221], v[6:9]
	v_mfma_f32_16x16x32_bf16 v[2:5], v[178:181], v[218:221], v[2:5]
	s_setprio 0
	s_barrier
	s_add_i32 s86, s86, 2
	s_add_u32 s34, s34, 0x100
	s_addc_u32 s35, s35, 0
	s_cmp_gt_u32 s86, 13
	s_cbranch_scc0 .LBB0_861
	s_and_b64 vcc, exec, s[20:21]
	s_cbranch_vccz .LBB0_864
	s_barrier

.LBB0_915:
	s_add_u32 s4, s34, s36
	s_addc_u32 s5, s35, s37
	s_add_u32 s42, s4, 0x100
	s_addc_u32 s43, s5, 0
	s_add_u32 s40, s76, s36
	s_addc_u32 s41, s78, s37
	s_add_u32 s4, s4, 0x180
	s_addc_u32 s5, s5, 0
	s_add_i32 s85, 0, 0x10000
	s_add_i32 vcc_lo, 0, 0x14000
	v_add_u32_e32 v138, s85, v231
	v_add_u32_e32 v162, vcc_lo, v231
	ds_read_b128 v[126:129], v138
	ds_read_b128 v[130:133], v138 offset:1024
	ds_read_b128 v[134:137], v138 offset:2048
	ds_read_b128 v[138:141], v138 offset:3072
	ds_read_b128 v[142:145], v162
	ds_read_b128 v[146:149], v162 offset:1024
	ds_read_b128 v[158:161], v162 offset:2048
	ds_read_b128 v[162:165], v162 offset:3072
	s_cmpk_eq_i32 s36, 0x1f00
	s_cselect_b32 s39, s75, s5
	s_cselect_b32 s38, s74, s4
	s_cselect_b32 s41, s25, s41
	s_cselect_b32 s40, s73, s40
	s_cselect_b32 s43, s27, s43
	s_cselect_b32 s42, s72, s42
	v_lshl_add_u64 v[194:195], v[118:119], 0, s[36:37]
	s_add_i32 m0, s58, 0xc000
	ds_read_b128 v[166:169], v242
	ds_read_b128 v[170:173], v242 offset:1024
	ds_read_b128 v[174:177], v242 offset:2048
	ds_read_b128 v[178:181], v242 offset:3072
	ds_read_b128 v[182:185], v242 offset:4096
	ds_read_b128 v[186:189], v242 offset:5120
	ds_read_b128 v[208:211], v242 offset:6144
	ds_read_b128 v[212:215], v242 offset:7168
	global_load_lds_dwordx4 v[194:195], off
	v_lshl_add_u64 v[194:195], v[120:121], 0, s[36:37]
	s_add_i32 m0, s58, 0xe000
	s_nop 0
	global_load_lds_dwordx4 v[194:195], off
	s_waitcnt vmcnt(8)
	s_waitcnt lgkmcnt(0)
	s_barrier
	s_setprio 1
	s_waitcnt lgkmcnt(0)
	v_mfma_f32_16x16x32_bf16 v[154:157], v[126:129], v[166:169], v[154:157]
	v_mfma_f32_16x16x32_bf16 v[150:153], v[134:137], v[166:169], v[150:153]
	v_mfma_f32_16x16x32_bf16 v[110:113], v[126:129], v[174:177], v[110:113]
	v_mfma_f32_16x16x32_bf16 v[106:109], v[134:137], v[174:177], v[106:109]
	v_mfma_f32_16x16x32_bf16 v[94:97], v[126:129], v[182:185], v[94:97]
	v_mfma_f32_16x16x32_bf16 v[90:93], v[134:137], v[182:185], v[90:93]
	v_mfma_f32_16x16x32_bf16 v[78:81], v[126:129], v[208:211], v[78:81]
	v_mfma_f32_16x16x32_bf16 v[74:77], v[134:137], v[208:211], v[74:77]
	v_mfma_f32_16x16x32_bf16 v[154:157], v[130:133], v[170:173], v[154:157]
	v_mfma_f32_16x16x32_bf16 v[150:153], v[138:141], v[170:173], v[150:153]
	v_mfma_f32_16x16x32_bf16 v[110:113], v[130:133], v[178:181], v[110:113]
	v_mfma_f32_16x16x32_bf16 v[106:109], v[138:141], v[178:181], v[106:109]
	v_mfma_f32_16x16x32_bf16 v[94:97], v[130:133], v[186:189], v[94:97]
	v_mfma_f32_16x16x32_bf16 v[90:93], v[138:141], v[186:189], v[90:93]
	v_mfma_f32_16x16x32_bf16 v[78:81], v[130:133], v[212:215], v[78:81]
	v_mfma_f32_16x16x32_bf16 v[74:77], v[138:141], v[212:215], v[74:77]
	s_setprio 0
	s_setprio 1
	v_mfma_f32_16x16x32_bf16 v[122:125], v[142:145], v[166:169], v[122:125]
	v_mfma_f32_16x16x32_bf16 v[114:117], v[158:161], v[166:169], v[114:117]
	v_mfma_f32_16x16x32_bf16 v[102:105], v[142:145], v[174:177], v[102:105]
	v_mfma_f32_16x16x32_bf16 v[98:101], v[158:161], v[174:177], v[98:101]
	v_mfma_f32_16x16x32_bf16 v[86:89], v[142:145], v[182:185], v[86:89]
	v_mfma_f32_16x16x32_bf16 v[82:85], v[158:161], v[182:185], v[82:85]
	v_mfma_f32_16x16x32_bf16 v[70:73], v[142:145], v[208:211], v[70:73]
	v_mfma_f32_16x16x32_bf16 v[66:69], v[158:161], v[208:211], v[66:69]
	v_mfma_f32_16x16x32_bf16 v[122:125], v[146:149], v[170:173], v[122:125]
	v_mfma_f32_16x16x32_bf16 v[114:117], v[162:165], v[170:173], v[114:117]
	v_mfma_f32_16x16x32_bf16 v[102:105], v[146:149], v[178:181], v[102:105]
	v_mfma_f32_16x16x32_bf16 v[98:101], v[162:165], v[178:181], v[98:101]
	v_mfma_f32_16x16x32_bf16 v[86:89], v[146:149], v[186:189], v[86:89]
	v_mfma_f32_16x16x32_bf16 v[82:85], v[162:165], v[186:189], v[82:85]
	v_mfma_f32_16x16x32_bf16 v[70:73], v[146:149], v[212:215], v[70:73]
	v_mfma_f32_16x16x32_bf16 v[66:69], v[162:165], v[212:215], v[66:69]
	s_setprio 0
	s_barrier
	s_add_i32 s4, s85, s57
	v_lshl_add_u64 v[194:195], s[40:41], 0, v[0:1]
	s_mov_b32 m0, s4
	ds_read_b128 v[166:169], v242 offset:16384
	ds_read_b128 v[170:173], v242 offset:17408
	ds_read_b128 v[174:177], v242 offset:18432
	ds_read_b128 v[178:181], v242 offset:19456
	ds_read_b128 v[182:185], v242 offset:20480
	ds_read_b128 v[186:189], v242 offset:21504
	ds_read_b128 v[208:211], v242 offset:22528
	ds_read_b128 v[212:215], v242 offset:23552
	global_load_lds_dwordx4 v[194:195], off
	s_add_i32 m0, s4, 0x2000
	s_add_u32 s86, s40, 0x100000
	v_lshl_add_u64 v[198:199], s[40:41], 0, v[190:191]
	s_addc_u32 s87, s41, 0
	s_add_i32 s4, vcc_lo, s57
	global_load_lds_dwordx4 v[198:199], off
	s_mov_b32 m0, s4
	s_nop 0
	global_load_lds_dwordx4 v0, s[86:87]
	s_add_i32 m0, s4, 0x2000
	s_nop 0
	global_load_lds_dwordx4 v190, s[86:87]
	s_mov_b32 m0, s58
	s_nop 0
	global_load_lds_dwordx4 v202, s[42:43]
	s_mov_b32 m0, s59
	s_nop 0
	global_load_lds_dwordx4 v192, s[42:43]
	s_waitcnt vmcnt(8)
	s_waitcnt lgkmcnt(0)
	s_barrier
	s_setprio 1
	s_waitcnt lgkmcnt(0)
	v_mfma_f32_16x16x32_bf16 v[62:65], v[126:129], v[166:169], v[62:65]
	v_mfma_f32_16x16x32_bf16 v[58:61], v[134:137], v[166:169], v[58:61]
	v_mfma_f32_16x16x32_bf16 v[46:49], v[126:129], v[174:177], v[46:49]
	v_mfma_f32_16x16x32_bf16 v[42:45], v[134:137], v[174:177], v[42:45]
	v_mfma_f32_16x16x32_bf16 v[30:33], v[126:129], v[182:185], v[30:33]
	v_mfma_f32_16x16x32_bf16 v[26:29], v[134:137], v[182:185], v[26:29]
	v_mfma_f32_16x16x32_bf16 v[14:17], v[126:129], v[208:211], v[14:17]
	v_mfma_f32_16x16x32_bf16 v[10:13], v[134:137], v[208:211], v[10:13]
	v_mfma_f32_16x16x32_bf16 v[62:65], v[130:133], v[170:173], v[62:65]
	v_mfma_f32_16x16x32_bf16 v[58:61], v[138:141], v[170:173], v[58:61]
	v_mfma_f32_16x16x32_bf16 v[46:49], v[130:133], v[178:181], v[46:49]
	v_mfma_f32_16x16x32_bf16 v[42:45], v[138:141], v[178:181], v[42:45]
	v_mfma_f32_16x16x32_bf16 v[30:33], v[130:133], v[186:189], v[30:33]
	v_mfma_f32_16x16x32_bf16 v[26:29], v[138:141], v[186:189], v[26:29]
	v_mfma_f32_16x16x32_bf16 v[14:17], v[130:133], v[212:215], v[14:17]
	v_mfma_f32_16x16x32_bf16 v[10:13], v[138:141], v[212:215], v[10:13]
	s_setprio 0
	s_setprio 1
	v_mfma_f32_16x16x32_bf16 v[54:57], v[142:145], v[166:169], v[54:57]
	v_mfma_f32_16x16x32_bf16 v[50:53], v[158:161], v[166:169], v[50:53]
	v_mfma_f32_16x16x32_bf16 v[38:41], v[142:145], v[174:177], v[38:41]
	v_mfma_f32_16x16x32_bf16 v[34:37], v[158:161], v[174:177], v[34:37]
	v_mfma_f32_16x16x32_bf16 v[22:25], v[142:145], v[182:185], v[22:25]
	v_mfma_f32_16x16x32_bf16 v[18:21], v[158:161], v[182:185], v[18:21]
	v_mfma_f32_16x16x32_bf16 v[6:9], v[142:145], v[208:211], v[6:9]
	v_mfma_f32_16x16x32_bf16 v[2:5], v[158:161], v[208:211], v[2:5]
	v_mfma_f32_16x16x32_bf16 v[54:57], v[146:149], v[170:173], v[54:57]
	v_mfma_f32_16x16x32_bf16 v[50:53], v[162:165], v[170:173], v[50:53]
	v_mfma_f32_16x16x32_bf16 v[38:41], v[146:149], v[178:181], v[38:41]
	v_mfma_f32_16x16x32_bf16 v[34:37], v[162:165], v[178:181], v[34:37]
	v_mfma_f32_16x16x32_bf16 v[22:25], v[146:149], v[186:189], v[22:25]
	v_mfma_f32_16x16x32_bf16 v[18:21], v[162:165], v[186:189], v[18:21]
	v_mfma_f32_16x16x32_bf16 v[6:9], v[146:149], v[212:215], v[6:9]
	v_mfma_f32_16x16x32_bf16 v[2:5], v[162:165], v[212:215], v[2:5]
	s_setprio 0
	s_barrier
	s_add_i32 s4, 0, 0x18000
	s_add_i32 s5, 0, 0x1c000
	v_add_u32_e32 v138, s4, v231
	v_add_u32_e32 v162, s5, v231
	ds_read_b128 v[126:129], v138
	ds_read_b128 v[130:133], v138 offset:1024
	ds_read_b128 v[134:137], v138 offset:2048
	ds_read_b128 v[138:141], v138 offset:3072
	ds_read_b128 v[142:145], v162
	ds_read_b128 v[146:149], v162 offset:1024
	ds_read_b128 v[158:161], v162 offset:2048
	ds_read_b128 v[162:165], v162 offset:3072
	s_add_u32 s42, s42, 0x100000
	s_addc_u32 s43, s43, 0
	s_mov_b32 m0, s65
	ds_read_b128 v[166:169], v242 offset:32768
	ds_read_b128 v[170:173], v242 offset:33792
	ds_read_b128 v[174:177], v242 offset:34816
	ds_read_b128 v[178:181], v242 offset:35840
	ds_read_b128 v[182:185], v242 offset:36864
	ds_read_b128 v[186:189], v242 offset:37888
	ds_read_b128 v[208:211], v242 offset:38912
	ds_read_b128 v[212:215], v242 offset:39936
	global_load_lds_dwordx4 v202, s[42:43]
	s_mov_b32 m0, s68
	s_nop 0
	global_load_lds_dwordx4 v192, s[42:43]
	s_waitcnt vmcnt(8)
	s_waitcnt lgkmcnt(0)
	s_barrier
	s_setprio 1
	s_waitcnt lgkmcnt(0)
	v_mfma_f32_16x16x32_bf16 v[154:157], v[126:129], v[166:169], v[154:157]
	v_mfma_f32_16x16x32_bf16 v[150:153], v[134:137], v[166:169], v[150:153]
	v_mfma_f32_16x16x32_bf16 v[110:113], v[126:129], v[174:177], v[110:113]
	v_mfma_f32_16x16x32_bf16 v[106:109], v[134:137], v[174:177], v[106:109]
	v_mfma_f32_16x16x32_bf16 v[94:97], v[126:129], v[182:185], v[94:97]
	v_mfma_f32_16x16x32_bf16 v[90:93], v[134:137], v[182:185], v[90:93]
	v_mfma_f32_16x16x32_bf16 v[78:81], v[126:129], v[208:211], v[78:81]
	v_mfma_f32_16x16x32_bf16 v[74:77], v[134:137], v[208:211], v[74:77]
	v_mfma_f32_16x16x32_bf16 v[154:157], v[130:133], v[170:173], v[154:157]
	v_mfma_f32_16x16x32_bf16 v[150:153], v[138:141], v[170:173], v[150:153]
	v_mfma_f32_16x16x32_bf16 v[110:113], v[130:133], v[178:181], v[110:113]
	v_mfma_f32_16x16x32_bf16 v[106:109], v[138:141], v[178:181], v[106:109]
	v_mfma_f32_16x16x32_bf16 v[94:97], v[130:133], v[186:189], v[94:97]
	v_mfma_f32_16x16x32_bf16 v[90:93], v[138:141], v[186:189], v[90:93]
	v_mfma_f32_16x16x32_bf16 v[78:81], v[130:133], v[212:215], v[78:81]
	v_mfma_f32_16x16x32_bf16 v[74:77], v[138:141], v[212:215], v[74:77]
	s_setprio 0
	s_setprio 1
	v_mfma_f32_16x16x32_bf16 v[122:125], v[142:145], v[166:169], v[122:125]
	v_mfma_f32_16x16x32_bf16 v[114:117], v[158:161], v[166:169], v[114:117]
	v_mfma_f32_16x16x32_bf16 v[102:105], v[142:145], v[174:177], v[102:105]
	v_mfma_f32_16x16x32_bf16 v[98:101], v[158:161], v[174:177], v[98:101]
	v_mfma_f32_16x16x32_bf16 v[86:89], v[142:145], v[182:185], v[86:89]
	v_mfma_f32_16x16x32_bf16 v[82:85], v[158:161], v[182:185], v[82:85]
	v_mfma_f32_16x16x32_bf16 v[70:73], v[142:145], v[208:211], v[70:73]
	v_mfma_f32_16x16x32_bf16 v[66:69], v[158:161], v[208:211], v[66:69]
	v_mfma_f32_16x16x32_bf16 v[122:125], v[146:149], v[170:173], v[122:125]
	v_mfma_f32_16x16x32_bf16 v[114:117], v[162:165], v[170:173], v[114:117]
	v_mfma_f32_16x16x32_bf16 v[102:105], v[146:149], v[178:181], v[102:105]
	v_mfma_f32_16x16x32_bf16 v[98:101], v[162:165], v[178:181], v[98:101]
	v_mfma_f32_16x16x32_bf16 v[86:89], v[146:149], v[186:189], v[86:89]
	v_mfma_f32_16x16x32_bf16 v[82:85], v[162:165], v[186:189], v[82:85]
	v_mfma_f32_16x16x32_bf16 v[70:73], v[146:149], v[212:215], v[70:73]
	v_mfma_f32_16x16x32_bf16 v[66:69], v[162:165], v[212:215], v[66:69]
	s_setprio 0
	s_barrier
	s_add_i32 s4, s4, s57
	v_lshl_add_u64 v[194:195], v[194:195], 0, s[90:91]
	s_mov_b32 m0, s4
	ds_read_b128 v[166:169], v242 offset:49152
	ds_read_b128 v[170:173], v242 offset:50176
	ds_read_b128 v[174:177], v242 offset:51200
	ds_read_b128 v[178:181], v242 offset:52224
	ds_read_b128 v[182:185], v242 offset:53248
	ds_read_b128 v[186:189], v242 offset:54272
	ds_read_b128 v[208:211], v242 offset:55296
	ds_read_b128 v[212:215], v242 offset:56320
	global_load_lds_dwordx4 v[194:195], off
	s_add_i32 m0, s4, 0x2000
	s_add_u32 s40, s40, 0x100080
	v_lshl_add_u64 v[194:195], v[198:199], 0, s[90:91]
	s_addc_u32 s41, s41, 0
	s_add_i32 s4, s5, s57
	global_load_lds_dwordx4 v[194:195], off
	s_mov_b32 m0, s4
	s_nop 0
	global_load_lds_dwordx4 v0, s[40:41]
	s_add_i32 m0, s4, 0x2000
	s_nop 0
	global_load_lds_dwordx4 v190, s[40:41]
	s_mov_b32 m0, s54
	s_nop 0
	global_load_lds_dwordx4 v202, s[38:39]
	s_mov_b32 m0, s55
	s_nop 0
	global_load_lds_dwordx4 v192, s[38:39]
	s_waitcnt vmcnt(8)
	s_waitcnt lgkmcnt(0)
	s_barrier
	s_setprio 1
	s_waitcnt lgkmcnt(0)
	v_mfma_f32_16x16x32_bf16 v[62:65], v[126:129], v[166:169], v[62:65]
	v_mfma_f32_16x16x32_bf16 v[58:61], v[134:137], v[166:169], v[58:61]
	v_mfma_f32_16x16x32_bf16 v[46:49], v[126:129], v[174:177], v[46:49]
	v_mfma_f32_16x16x32_bf16 v[42:45], v[134:137], v[174:177], v[42:45]
	v_mfma_f32_16x16x32_bf16 v[30:33], v[126:129], v[182:185], v[30:33]
	v_mfma_f32_16x16x32_bf16 v[26:29], v[134:137], v[182:185], v[26:29]
	v_mfma_f32_16x16x32_bf16 v[14:17], v[126:129], v[208:211], v[14:17]
	v_mfma_f32_16x16x32_bf16 v[10:13], v[134:137], v[208:211], v[10:13]
	v_mfma_f32_16x16x32_bf16 v[62:65], v[130:133], v[170:173], v[62:65]
	v_mfma_f32_16x16x32_bf16 v[58:61], v[138:141], v[170:173], v[58:61]
	v_mfma_f32_16x16x32_bf16 v[46:49], v[130:133], v[178:181], v[46:49]
	v_mfma_f32_16x16x32_bf16 v[42:45], v[138:141], v[178:181], v[42:45]
	v_mfma_f32_16x16x32_bf16 v[30:33], v[130:133], v[186:189], v[30:33]
	v_mfma_f32_16x16x32_bf16 v[26:29], v[138:141], v[186:189], v[26:29]
	v_mfma_f32_16x16x32_bf16 v[14:17], v[130:133], v[212:215], v[14:17]
	v_mfma_f32_16x16x32_bf16 v[10:13], v[138:141], v[212:215], v[10:13]
	s_setprio 0
	s_setprio 1
	v_mfma_f32_16x16x32_bf16 v[54:57], v[142:145], v[166:169], v[54:57]
	v_mfma_f32_16x16x32_bf16 v[50:53], v[158:161], v[166:169], v[50:53]
	v_mfma_f32_16x16x32_bf16 v[38:41], v[142:145], v[174:177], v[38:41]
	v_mfma_f32_16x16x32_bf16 v[34:37], v[158:161], v[174:177], v[34:37]
	v_mfma_f32_16x16x32_bf16 v[22:25], v[142:145], v[182:185], v[22:25]
	v_mfma_f32_16x16x32_bf16 v[18:21], v[158:161], v[182:185], v[18:21]
	v_mfma_f32_16x16x32_bf16 v[6:9], v[142:145], v[208:211], v[6:9]
	v_mfma_f32_16x16x32_bf16 v[2:5], v[158:161], v[208:211], v[2:5]
	v_mfma_f32_16x16x32_bf16 v[54:57], v[146:149], v[170:173], v[54:57]
	v_mfma_f32_16x16x32_bf16 v[50:53], v[162:165], v[170:173], v[50:53]
	v_mfma_f32_16x16x32_bf16 v[38:41], v[146:149], v[178:181], v[38:41]
	v_mfma_f32_16x16x32_bf16 v[34:37], v[162:165], v[178:181], v[34:37]
	v_mfma_f32_16x16x32_bf16 v[22:25], v[146:149], v[186:189], v[22:25]
	v_mfma_f32_16x16x32_bf16 v[18:21], v[162:165], v[186:189], v[18:21]
	v_mfma_f32_16x16x32_bf16 v[6:9], v[146:149], v[212:215], v[6:9]
	v_mfma_f32_16x16x32_bf16 v[2:5], v[162:165], v[212:215], v[2:5]
	s_setprio 0
	s_barrier
	s_add_i32 s84, s84, 2
	s_add_u32 s36, s36, 0x100
	s_addc_u32 s37, s37, 0
	s_cmp_gt_u32 s84, 61
	s_cbranch_scc0 .LBB0_915
	s_and_b64 vcc, exec, s[20:21]
	s_cbranch_vccz .LBB0_918
	s_barrier

.LBB0_953:
	s_add_u32 s4, s24, s26
	s_addc_u32 s5, s25, s27
	s_add_u32 s34, s4, 0x100
	s_addc_u32 s35, s5, 0
	s_add_u32 s30, s68, s26
	s_addc_u32 s31, s69, s27
	s_add_u32 s4, s4, 0x180
	s_addc_u32 s5, s5, 0
	s_add_i32 s71, 0, 0x10000
	s_add_i32 s74, 0, 0x14000
	v_add_u32_e32 v146, s71, v229
	v_add_u32_e32 v162, s74, v229
	ds_read_b128 v[134:137], v146
	ds_read_b128 v[138:141], v146 offset:1024
	ds_read_b128 v[142:145], v146 offset:2048
	ds_read_b128 v[146:149], v146 offset:3072
	ds_read_b128 v[150:153], v162
	ds_read_b128 v[154:157], v162 offset:1024
	ds_read_b128 v[158:161], v162 offset:2048
	ds_read_b128 v[162:165], v162 offset:3072
	s_cmpk_eq_i32 s26, 0x1f00
	s_cselect_b32 s29, s65, s5
	s_cselect_b32 s28, s59, s4
	s_cselect_b32 s31, s17, s31
	s_cselect_b32 s30, s58, s30
	s_cselect_b32 s35, s19, s35
	s_cselect_b32 s34, s57, s34
	v_lshl_add_u64 v[194:195], v[122:123], 0, s[26:27]
	s_add_i32 m0, s37, 0xc000
	ds_read_b128 v[166:169], v231
	ds_read_b128 v[170:173], v231 offset:1024
	ds_read_b128 v[174:177], v231 offset:2048
	ds_read_b128 v[178:181], v231 offset:3072
	ds_read_b128 v[182:185], v231 offset:4096
	ds_read_b128 v[186:189], v231 offset:5120
	ds_read_b128 v[190:193], v231 offset:6144
	ds_read_b128 v[212:215], v231 offset:7168
	global_load_lds_dwordx4 v[194:195], off
	v_lshl_add_u64 v[194:195], v[124:125], 0, s[26:27]
	s_add_i32 m0, s37, 0xe000
	s_nop 0
	global_load_lds_dwordx4 v[194:195], off
	s_waitcnt vmcnt(8)
	s_waitcnt lgkmcnt(0)
	s_barrier
	s_setprio 1
	s_waitcnt lgkmcnt(0)
	v_mfma_f32_16x16x32_bf16 v[130:133], v[134:137], v[166:169], v[130:133]
	v_mfma_f32_16x16x32_bf16 v[126:129], v[142:145], v[166:169], v[126:129]
	v_mfma_f32_16x16x32_bf16 v[110:113], v[134:137], v[174:177], v[110:113]
	v_mfma_f32_16x16x32_bf16 v[106:109], v[142:145], v[174:177], v[106:109]
	v_mfma_f32_16x16x32_bf16 v[94:97], v[134:137], v[182:185], v[94:97]
	v_mfma_f32_16x16x32_bf16 v[90:93], v[142:145], v[182:185], v[90:93]
	v_mfma_f32_16x16x32_bf16 v[78:81], v[134:137], v[190:193], v[78:81]
	v_mfma_f32_16x16x32_bf16 v[74:77], v[142:145], v[190:193], v[74:77]
	v_mfma_f32_16x16x32_bf16 v[130:133], v[138:141], v[170:173], v[130:133]
	v_mfma_f32_16x16x32_bf16 v[126:129], v[146:149], v[170:173], v[126:129]
	v_mfma_f32_16x16x32_bf16 v[110:113], v[138:141], v[178:181], v[110:113]
	v_mfma_f32_16x16x32_bf16 v[106:109], v[146:149], v[178:181], v[106:109]
	v_mfma_f32_16x16x32_bf16 v[94:97], v[138:141], v[186:189], v[94:97]
	v_mfma_f32_16x16x32_bf16 v[90:93], v[146:149], v[186:189], v[90:93]
	v_mfma_f32_16x16x32_bf16 v[78:81], v[138:141], v[212:215], v[78:81]
	v_mfma_f32_16x16x32_bf16 v[74:77], v[146:149], v[212:215], v[74:77]
	s_setprio 0
	s_setprio 1
	v_mfma_f32_16x16x32_bf16 v[118:121], v[150:153], v[166:169], v[118:121]
	v_mfma_f32_16x16x32_bf16 v[114:117], v[158:161], v[166:169], v[114:117]
	v_mfma_f32_16x16x32_bf16 v[102:105], v[150:153], v[174:177], v[102:105]
	v_mfma_f32_16x16x32_bf16 v[98:101], v[158:161], v[174:177], v[98:101]
	v_mfma_f32_16x16x32_bf16 v[86:89], v[150:153], v[182:185], v[86:89]
	v_mfma_f32_16x16x32_bf16 v[82:85], v[158:161], v[182:185], v[82:85]
	v_mfma_f32_16x16x32_bf16 v[70:73], v[150:153], v[190:193], v[70:73]
	v_mfma_f32_16x16x32_bf16 v[66:69], v[158:161], v[190:193], v[66:69]
	v_mfma_f32_16x16x32_bf16 v[118:121], v[154:157], v[170:173], v[118:121]
	v_mfma_f32_16x16x32_bf16 v[114:117], v[162:165], v[170:173], v[114:117]
	v_mfma_f32_16x16x32_bf16 v[102:105], v[154:157], v[178:181], v[102:105]
	v_mfma_f32_16x16x32_bf16 v[98:101], v[162:165], v[178:181], v[98:101]
	v_mfma_f32_16x16x32_bf16 v[86:89], v[154:157], v[186:189], v[86:89]
	v_mfma_f32_16x16x32_bf16 v[82:85], v[162:165], v[186:189], v[82:85]
	v_mfma_f32_16x16x32_bf16 v[70:73], v[154:157], v[212:215], v[70:73]
	v_mfma_f32_16x16x32_bf16 v[66:69], v[162:165], v[212:215], v[66:69]
	s_setprio 0
	s_barrier
	s_add_i32 s4, s71, s36
	v_lshl_add_u64 v[194:195], s[30:31], 0, v[0:1]
	s_mov_b32 m0, s4
	ds_read_b128 v[166:169], v231 offset:16384
	ds_read_b128 v[170:173], v231 offset:17408
	ds_read_b128 v[174:177], v231 offset:18432
	ds_read_b128 v[178:181], v231 offset:19456
	ds_read_b128 v[182:185], v231 offset:20480
	ds_read_b128 v[186:189], v231 offset:21504
	ds_read_b128 v[190:193], v231 offset:22528
	ds_read_b128 v[212:215], v231 offset:23552
	global_load_lds_dwordx4 v[194:195], off
	s_add_i32 m0, s4, 0x2000
	s_add_u32 s72, s30, 0x100000
	v_lshl_add_u64 v[198:199], s[30:31], 0, v[202:203]
	s_addc_u32 s73, s31, 0
	s_add_i32 s4, s74, s36
	global_load_lds_dwordx4 v[198:199], off
	s_mov_b32 m0, s4
	s_nop 0
	global_load_lds_dwordx4 v0, s[72:73]
	s_add_i32 m0, s4, 0x2000
	s_nop 0
	global_load_lds_dwordx4 v202, s[72:73]
	s_mov_b32 m0, s37
	s_nop 0
	global_load_lds_dwordx4 v206, s[34:35]
	s_mov_b32 m0, s38
	s_nop 0
	global_load_lds_dwordx4 v204, s[34:35]
	s_waitcnt vmcnt(8)
	s_waitcnt lgkmcnt(0)
	s_barrier
	s_setprio 1
	s_waitcnt lgkmcnt(0)
	v_mfma_f32_16x16x32_bf16 v[62:65], v[134:137], v[166:169], v[62:65]
	v_mfma_f32_16x16x32_bf16 v[58:61], v[142:145], v[166:169], v[58:61]
	v_mfma_f32_16x16x32_bf16 v[46:49], v[134:137], v[174:177], v[46:49]
	v_mfma_f32_16x16x32_bf16 v[42:45], v[142:145], v[174:177], v[42:45]
	v_mfma_f32_16x16x32_bf16 v[30:33], v[134:137], v[182:185], v[30:33]
	v_mfma_f32_16x16x32_bf16 v[26:29], v[142:145], v[182:185], v[26:29]
	v_mfma_f32_16x16x32_bf16 v[14:17], v[134:137], v[190:193], v[14:17]
	v_mfma_f32_16x16x32_bf16 v[10:13], v[142:145], v[190:193], v[10:13]
	v_mfma_f32_16x16x32_bf16 v[62:65], v[138:141], v[170:173], v[62:65]
	v_mfma_f32_16x16x32_bf16 v[58:61], v[146:149], v[170:173], v[58:61]
	v_mfma_f32_16x16x32_bf16 v[46:49], v[138:141], v[178:181], v[46:49]
	v_mfma_f32_16x16x32_bf16 v[42:45], v[146:149], v[178:181], v[42:45]
	v_mfma_f32_16x16x32_bf16 v[30:33], v[138:141], v[186:189], v[30:33]
	v_mfma_f32_16x16x32_bf16 v[26:29], v[146:149], v[186:189], v[26:29]
	v_mfma_f32_16x16x32_bf16 v[14:17], v[138:141], v[212:215], v[14:17]
	v_mfma_f32_16x16x32_bf16 v[10:13], v[146:149], v[212:215], v[10:13]
	s_setprio 0
	s_setprio 1
	v_mfma_f32_16x16x32_bf16 v[54:57], v[150:153], v[166:169], v[54:57]
	v_mfma_f32_16x16x32_bf16 v[50:53], v[158:161], v[166:169], v[50:53]
	v_mfma_f32_16x16x32_bf16 v[38:41], v[150:153], v[174:177], v[38:41]
	v_mfma_f32_16x16x32_bf16 v[34:37], v[158:161], v[174:177], v[34:37]
	v_mfma_f32_16x16x32_bf16 v[22:25], v[150:153], v[182:185], v[22:25]
	v_mfma_f32_16x16x32_bf16 v[18:21], v[158:161], v[182:185], v[18:21]
	v_mfma_f32_16x16x32_bf16 v[6:9], v[150:153], v[190:193], v[6:9]
	v_mfma_f32_16x16x32_bf16 v[2:5], v[158:161], v[190:193], v[2:5]
	v_mfma_f32_16x16x32_bf16 v[54:57], v[154:157], v[170:173], v[54:57]
	v_mfma_f32_16x16x32_bf16 v[50:53], v[162:165], v[170:173], v[50:53]
	v_mfma_f32_16x16x32_bf16 v[38:41], v[154:157], v[178:181], v[38:41]
	v_mfma_f32_16x16x32_bf16 v[34:37], v[162:165], v[178:181], v[34:37]
	v_mfma_f32_16x16x32_bf16 v[22:25], v[154:157], v[186:189], v[22:25]
	v_mfma_f32_16x16x32_bf16 v[18:21], v[162:165], v[186:189], v[18:21]
	v_mfma_f32_16x16x32_bf16 v[6:9], v[154:157], v[212:215], v[6:9]
	v_mfma_f32_16x16x32_bf16 v[2:5], v[162:165], v[212:215], v[2:5]
	s_setprio 0
	s_barrier
	s_add_i32 s4, 0, 0x18000
	s_add_i32 s5, 0, 0x1c000
	v_add_u32_e32 v146, s4, v229
	v_add_u32_e32 v162, s5, v229
	ds_read_b128 v[134:137], v146
	ds_read_b128 v[138:141], v146 offset:1024
	ds_read_b128 v[142:145], v146 offset:2048
	ds_read_b128 v[146:149], v146 offset:3072
	ds_read_b128 v[150:153], v162
	ds_read_b128 v[154:157], v162 offset:1024
	ds_read_b128 v[158:161], v162 offset:2048
	ds_read_b128 v[162:165], v162 offset:3072
	s_add_u32 s34, s34, 0x100000
	s_addc_u32 s35, s35, 0
	s_mov_b32 m0, s39
	ds_read_b128 v[166:169], v231 offset:32768
	ds_read_b128 v[170:173], v231 offset:33792
	ds_read_b128 v[174:177], v231 offset:34816
	ds_read_b128 v[178:181], v231 offset:35840
	ds_read_b128 v[182:185], v231 offset:36864
	ds_read_b128 v[186:189], v231 offset:37888
	ds_read_b128 v[190:193], v231 offset:38912
	ds_read_b128 v[212:215], v231 offset:39936
	global_load_lds_dwordx4 v206, s[34:35]
	s_mov_b32 m0, s40
	s_nop 0
	global_load_lds_dwordx4 v204, s[34:35]
	s_waitcnt vmcnt(8)
	s_waitcnt lgkmcnt(0)
	s_barrier
	s_setprio 1
	s_waitcnt lgkmcnt(0)
	v_mfma_f32_16x16x32_bf16 v[130:133], v[134:137], v[166:169], v[130:133]
	v_mfma_f32_16x16x32_bf16 v[126:129], v[142:145], v[166:169], v[126:129]
	v_mfma_f32_16x16x32_bf16 v[110:113], v[134:137], v[174:177], v[110:113]
	v_mfma_f32_16x16x32_bf16 v[106:109], v[142:145], v[174:177], v[106:109]
	v_mfma_f32_16x16x32_bf16 v[94:97], v[134:137], v[182:185], v[94:97]
	v_mfma_f32_16x16x32_bf16 v[90:93], v[142:145], v[182:185], v[90:93]
	v_mfma_f32_16x16x32_bf16 v[78:81], v[134:137], v[190:193], v[78:81]
	v_mfma_f32_16x16x32_bf16 v[74:77], v[142:145], v[190:193], v[74:77]
	v_mfma_f32_16x16x32_bf16 v[130:133], v[138:141], v[170:173], v[130:133]
	v_mfma_f32_16x16x32_bf16 v[126:129], v[146:149], v[170:173], v[126:129]
	v_mfma_f32_16x16x32_bf16 v[110:113], v[138:141], v[178:181], v[110:113]
	v_mfma_f32_16x16x32_bf16 v[106:109], v[146:149], v[178:181], v[106:109]
	v_mfma_f32_16x16x32_bf16 v[94:97], v[138:141], v[186:189], v[94:97]
	v_mfma_f32_16x16x32_bf16 v[90:93], v[146:149], v[186:189], v[90:93]
	v_mfma_f32_16x16x32_bf16 v[78:81], v[138:141], v[212:215], v[78:81]
	v_mfma_f32_16x16x32_bf16 v[74:77], v[146:149], v[212:215], v[74:77]
	s_setprio 0
	s_setprio 1
	v_mfma_f32_16x16x32_bf16 v[118:121], v[150:153], v[166:169], v[118:121]
	v_mfma_f32_16x16x32_bf16 v[114:117], v[158:161], v[166:169], v[114:117]
	v_mfma_f32_16x16x32_bf16 v[102:105], v[150:153], v[174:177], v[102:105]
	v_mfma_f32_16x16x32_bf16 v[98:101], v[158:161], v[174:177], v[98:101]
	v_mfma_f32_16x16x32_bf16 v[86:89], v[150:153], v[182:185], v[86:89]
	v_mfma_f32_16x16x32_bf16 v[82:85], v[158:161], v[182:185], v[82:85]
	v_mfma_f32_16x16x32_bf16 v[70:73], v[150:153], v[190:193], v[70:73]
	v_mfma_f32_16x16x32_bf16 v[66:69], v[158:161], v[190:193], v[66:69]
	v_mfma_f32_16x16x32_bf16 v[118:121], v[154:157], v[170:173], v[118:121]
	v_mfma_f32_16x16x32_bf16 v[114:117], v[162:165], v[170:173], v[114:117]
	v_mfma_f32_16x16x32_bf16 v[102:105], v[154:157], v[178:181], v[102:105]
	v_mfma_f32_16x16x32_bf16 v[98:101], v[162:165], v[178:181], v[98:101]
	v_mfma_f32_16x16x32_bf16 v[86:89], v[154:157], v[186:189], v[86:89]
	v_mfma_f32_16x16x32_bf16 v[82:85], v[162:165], v[186:189], v[82:85]
	v_mfma_f32_16x16x32_bf16 v[70:73], v[154:157], v[212:215], v[70:73]
	v_mfma_f32_16x16x32_bf16 v[66:69], v[162:165], v[212:215], v[66:69]
	s_setprio 0
	s_barrier
	s_add_i32 s4, s4, s36
	v_lshl_add_u64 v[194:195], v[194:195], 0, s[90:91]
	s_mov_b32 m0, s4
	ds_read_b128 v[166:169], v231 offset:49152
	ds_read_b128 v[170:173], v231 offset:50176
	ds_read_b128 v[174:177], v231 offset:51200
	ds_read_b128 v[178:181], v231 offset:52224
	ds_read_b128 v[182:185], v231 offset:53248
	ds_read_b128 v[186:189], v231 offset:54272
	ds_read_b128 v[190:193], v231 offset:55296
	ds_read_b128 v[212:215], v231 offset:56320
	global_load_lds_dwordx4 v[194:195], off
	s_add_i32 m0, s4, 0x2000
	s_add_u32 s30, s30, 0x100080
	v_lshl_add_u64 v[194:195], v[198:199], 0, s[90:91]
	s_addc_u32 s31, s31, 0
	s_add_i32 s4, s5, s36
	global_load_lds_dwordx4 v[194:195], off
	s_mov_b32 m0, s4
	s_nop 0
	global_load_lds_dwordx4 v0, s[30:31]
	s_add_i32 m0, s4, 0x2000
	s_nop 0
	global_load_lds_dwordx4 v202, s[30:31]
	s_mov_b32 m0, s41
	s_nop 0
	global_load_lds_dwordx4 v206, s[28:29]
	s_mov_b32 m0, s42
	s_nop 0
	global_load_lds_dwordx4 v204, s[28:29]
	s_waitcnt vmcnt(8)
	s_waitcnt lgkmcnt(0)
	s_barrier
	s_setprio 1
	s_waitcnt lgkmcnt(0)
	v_mfma_f32_16x16x32_bf16 v[62:65], v[134:137], v[166:169], v[62:65]
	v_mfma_f32_16x16x32_bf16 v[58:61], v[142:145], v[166:169], v[58:61]
	v_mfma_f32_16x16x32_bf16 v[46:49], v[134:137], v[174:177], v[46:49]
	v_mfma_f32_16x16x32_bf16 v[42:45], v[142:145], v[174:177], v[42:45]
	v_mfma_f32_16x16x32_bf16 v[30:33], v[134:137], v[182:185], v[30:33]
	v_mfma_f32_16x16x32_bf16 v[26:29], v[142:145], v[182:185], v[26:29]
	v_mfma_f32_16x16x32_bf16 v[14:17], v[134:137], v[190:193], v[14:17]
	v_mfma_f32_16x16x32_bf16 v[10:13], v[142:145], v[190:193], v[10:13]
	v_mfma_f32_16x16x32_bf16 v[62:65], v[138:141], v[170:173], v[62:65]
	v_mfma_f32_16x16x32_bf16 v[58:61], v[146:149], v[170:173], v[58:61]
	v_mfma_f32_16x16x32_bf16 v[46:49], v[138:141], v[178:181], v[46:49]
	v_mfma_f32_16x16x32_bf16 v[42:45], v[146:149], v[178:181], v[42:45]
	v_mfma_f32_16x16x32_bf16 v[30:33], v[138:141], v[186:189], v[30:33]
	v_mfma_f32_16x16x32_bf16 v[26:29], v[146:149], v[186:189], v[26:29]
	v_mfma_f32_16x16x32_bf16 v[14:17], v[138:141], v[212:215], v[14:17]
	v_mfma_f32_16x16x32_bf16 v[10:13], v[146:149], v[212:215], v[10:13]
	s_setprio 0
	s_setprio 1
	v_mfma_f32_16x16x32_bf16 v[54:57], v[150:153], v[166:169], v[54:57]
	v_mfma_f32_16x16x32_bf16 v[50:53], v[158:161], v[166:169], v[50:53]
	v_mfma_f32_16x16x32_bf16 v[38:41], v[150:153], v[174:177], v[38:41]
	v_mfma_f32_16x16x32_bf16 v[34:37], v[158:161], v[174:177], v[34:37]
	v_mfma_f32_16x16x32_bf16 v[22:25], v[150:153], v[182:185], v[22:25]
	v_mfma_f32_16x16x32_bf16 v[18:21], v[158:161], v[182:185], v[18:21]
	v_mfma_f32_16x16x32_bf16 v[6:9], v[150:153], v[190:193], v[6:9]
	v_mfma_f32_16x16x32_bf16 v[2:5], v[158:161], v[190:193], v[2:5]
	v_mfma_f32_16x16x32_bf16 v[54:57], v[154:157], v[170:173], v[54:57]
	v_mfma_f32_16x16x32_bf16 v[50:53], v[162:165], v[170:173], v[50:53]
	v_mfma_f32_16x16x32_bf16 v[38:41], v[154:157], v[178:181], v[38:41]
	v_mfma_f32_16x16x32_bf16 v[34:37], v[162:165], v[178:181], v[34:37]
	v_mfma_f32_16x16x32_bf16 v[22:25], v[154:157], v[186:189], v[22:25]
	v_mfma_f32_16x16x32_bf16 v[18:21], v[162:165], v[186:189], v[18:21]
	v_mfma_f32_16x16x32_bf16 v[6:9], v[154:157], v[212:215], v[6:9]
	v_mfma_f32_16x16x32_bf16 v[2:5], v[162:165], v[212:215], v[2:5]
	s_setprio 0
	s_barrier
	s_add_i32 s70, s70, 2
	s_add_u32 s26, s26, 0x100
	s_addc_u32 s27, s27, 0
	s_cmp_gt_u32 s70, 61
	s_cbranch_scc0 .LBB0_953
	s_and_b64 vcc, exec, s[14:15]
	s_cbranch_vccz .LBB0_956
	s_barrier
